# projection GEMM epilogue: lower-bound and rmsnorm-gain vectors loaded once per unit and kept in dead fragment registers; later row groups copy them instead of reloading behind a full vmcnt(0)
# speedup vs baseline: 1.1402x; 1.0022x over previous
.LBB0_958:
	s_and_b64 vcc, exec, s[0:1]
	s_cbranch_vccz .LBB0_974
	v_mul_f32_e32 v0, v127, v127
	v_fmac_f32_e32 v0, v126, v126
	v_fmac_f32_e32 v0, v128, v128
	v_fmac_f32_e32 v0, v129, v129
	v_fmac_f32_e32 v0, v122, v122
	v_fmac_f32_e32 v0, v123, v123
	v_fmac_f32_e32 v0, v124, v124
	v_fmac_f32_e32 v0, v125, v125
	v_fmac_f32_e32 v0, v118, v118
	v_fmac_f32_e32 v0, v119, v119
	v_pk_mul_f32 v[130:131], v[120:121], v[120:121]
	v_pk_mul_f32 v[132:133], v[114:115], v[114:115]
	v_add_f32_e32 v0, v130, v0
	v_add_f32_e32 v0, v131, v0
	v_add_f32_e32 v0, v132, v0
	v_pk_mul_f32 v[130:131], v[116:117], v[116:117]
	v_add_f32_e32 v0, v133, v0
	v_add_f32_e32 v0, v130, v0
	v_add_f32_e32 v0, v131, v0
	v_and_b32_e32 v131, 64, v214
	v_xor_b32_e32 v130, 16, v214
	v_add_u32_e32 v131, 64, v131
	v_cmp_lt_i32_e32 vcc, v130, v131
	s_and_b64 s[0:1], s[42:43], exec
	s_cselect_b32 s1, s18, s20
	v_cndmask_b32_e32 v130, v214, v130, vcc
	v_lshlrev_b32_e32 v130, 2, v130
	ds_bpermute_b32 v130, v130, v0
	s_cselect_b32 s0, s17, s19
	s_lshr_b32 s6, s28, 2
	s_and_b32 s6, s6, 0x7f0
	s_waitcnt lgkmcnt(0)
	v_add_f32_e32 v0, v0, v130
	v_xor_b32_e32 v130, 32, v214
	v_cmp_lt_i32_e32 vcc, v130, v131
	v_or_b32_e32 v131, s6, v167
	v_lshlrev_b32_e32 v157, 3, v131
	v_cndmask_b32_e32 v130, v214, v130, vcc
	v_lshlrev_b32_e32 v130, 2, v130
	ds_bpermute_b32 v130, v130, v0
	v_cmp_gt_i32_e32 vcc, s81, v156
	s_waitcnt lgkmcnt(0)
	v_add_f32_e32 v0, v0, v130
	v_fmamk_f32 v0, v0, 0x3c800000, v208
	v_rsq_f32_e32 v130, v0
	v_lshlrev_b32_e32 v0, 2, v138
	global_load_dwordx4 v[158:161], v0, s[0:1]
	v_pk_mul_f32 v[132:133], v[126:127], v[130:131] op_sel_hi:[1,0]
	s_waitcnt vmcnt(0)
	v_mov_b64_e32 v[224:225], v[158:159]
	v_mov_b64_e32 v[226:227], v[160:161]
	v_pk_mul_f32 v[132:133], v[158:159], v[132:133]
	v_pk_mul_f32 v[158:159], v[128:129], v[130:131] op_sel_hi:[1,0]
	s_nop 0
	v_pk_mul_f32 v[162:163], v[160:161], v[158:159]
	s_and_saveexec_b64 s[6:7], vcc
	s_cbranch_execz .LBB0_961
	v_readlane_b32 s30, v254, 6
	v_readlane_b32 s31, v254, 7
	s_nop 4
	global_load_dwordx4 v[158:161], v157, s[30:31]
	s_waitcnt vmcnt(0)
	v_pk_mul_f32 v[172:173], v[132:133], v[158:159] op_sel:[1,1] op_sel_hi:[1,0]
	v_pk_mul_f32 v[164:165], v[132:133], v[158:159]
	v_pk_fma_f32 v[132:133], v[132:133], v[158:159], v[172:173] op_sel_hi:[0,1,1]
	v_mul_f32_e32 v132, v163, v161
	v_pk_fma_f32 v[158:159], v[162:163], v[160:161], v[132:133] op_sel_hi:[1,1,0] neg_lo:[0,0,1] neg_hi:[0,0,1]
	v_mul_f32_e32 v132, v163, v160
	v_pk_fma_f32 v[160:161], v[162:163], v[160:161], v[132:133] op_sel:[0,1,0] op_sel_hi:[1,0,0]
	v_sub_f32_e32 v132, v164, v172
	v_mov_b32_e32 v162, v158
	v_mov_b32_e32 v163, v160
.LBB0_961:
	s_or_b64 exec, exec, s[6:7]
	v_lshl_add_u64 v[158:159], s[0:1], 0, v[0:1]
	v_readlane_b32 s0, v254, 35
	v_readlane_b32 s1, v254, 36
	v_pk_mul_f32 v[172:173], v[154:155], v[132:133]
	v_lshlrev_b32_e32 v0, 1, v138
	v_mov_b64_e32 v[160:161], s[0:1]
	v_mad_i64_i32 v[160:161], s[0:1], v156, s52, v[160:161]
	s_lshl_b32 s0, s27, 1
	s_mov_b32 s1, s35
	v_lshl_add_u64 v[160:161], v[160:161], 0, s[0:1]
	v_lshl_add_u64 v[164:165], s[76:77], 1, v[160:161]
	v_mov_b32_e32 v160, v154
	v_mov_b32_e32 v161, v154
	v_pk_mul_f32 v[162:163], v[160:161], v[162:163]
	v_lshl_add_u64 v[132:133], v[164:165], 0, v[0:1]
	v_cvt_pk_bf16_f32 v164, v172, v173
	v_cvt_pk_bf16_f32 v165, v162, v163
	global_store_dwordx2 v[132:133], v[164:165], off
	global_load_dwordx4 v[162:165], v[158:159], off offset:64
	v_mov_b32_e32 v131, v130
	v_pk_mul_f32 v[172:173], v[122:123], v[130:131]
	s_waitcnt vmcnt(0)
	v_mov_b64_e32 v[228:229], v[162:163]
	v_mov_b64_e32 v[230:231], v[164:165]
	v_pk_mul_f32 v[162:163], v[172:173], v[162:163]
	v_pk_mul_f32 v[172:173], v[124:125], v[130:131]
	s_nop 0
	v_pk_mul_f32 v[164:165], v[172:173], v[164:165]
	s_and_saveexec_b64 s[0:1], vcc
	s_cbranch_execz .LBB0_963
	v_readlane_b32 s6, v254, 6
	v_readlane_b32 s7, v254, 7
	s_nop 4
	global_load_dwordx4 v[172:175], v157, s[6:7] offset:64
	s_waitcnt vmcnt(0)
	v_pk_mul_f32 v[178:179], v[162:163], v[172:173] op_sel:[1,1] op_sel_hi:[1,0]
	v_mul_f32_e32 v0, v165, v175
	v_pk_mul_f32 v[176:177], v[162:163], v[172:173]
	v_pk_fma_f32 v[162:163], v[162:163], v[172:173], v[178:179] op_sel_hi:[0,1,1]
	v_pk_fma_f32 v[172:173], v[164:165], v[174:175], v[0:1] op_sel_hi:[1,1,0] neg_lo:[0,0,1] neg_hi:[0,0,1]
	v_mul_f32_e32 v0, v165, v174
	v_pk_fma_f32 v[174:175], v[164:165], v[174:175], v[0:1] op_sel:[0,1,0] op_sel_hi:[1,0,0]
	v_sub_f32_e32 v162, v176, v178
	v_mov_b32_e32 v164, v172
	v_mov_b32_e32 v165, v174
.LBB0_963:
	s_or_b64 exec, exec, s[0:1]
	v_pk_mul_f32 v[160:161], v[160:161], v[164:165]
	v_pk_mul_f32 v[162:163], v[154:155], v[162:163]
	v_pk_mul_f32 v[164:165], v[118:119], v[130:131]
	v_cvt_pk_bf16_f32 v162, v162, v163
	v_cvt_pk_bf16_f32 v163, v160, v161
	global_store_dwordx2 v[132:133], v[162:163], off offset:32
	global_load_dwordx4 v[160:163], v[158:159], off offset:128
	s_waitcnt vmcnt(0)
	v_mov_b64_e32 v[232:233], v[160:161]
	v_mov_b64_e32 v[234:235], v[162:163]
	v_pk_mul_f32 v[160:161], v[164:165], v[160:161]
	v_pk_mul_f32 v[164:165], v[120:121], v[130:131]
	s_nop 0
	v_pk_mul_f32 v[164:165], v[164:165], v[162:163]
	s_and_saveexec_b64 s[0:1], vcc
	s_cbranch_execz .LBB0_965
	global_load_dwordx4 v[172:175], v[140:141], off
	s_waitcnt vmcnt(0)
	v_pk_mul_f32 v[176:177], v[160:161], v[172:173] op_sel:[1,1] op_sel_hi:[1,0]
	v_mul_f32_e32 v0, v165, v175
	v_pk_mul_f32 v[162:163], v[160:161], v[172:173]
	v_pk_fma_f32 v[160:161], v[160:161], v[172:173], v[176:177] op_sel_hi:[0,1,1]
	v_pk_fma_f32 v[172:173], v[164:165], v[174:175], v[0:1] op_sel_hi:[1,1,0] neg_lo:[0,0,1] neg_hi:[0,0,1]
	v_mul_f32_e32 v0, v165, v174
	v_pk_fma_f32 v[174:175], v[164:165], v[174:175], v[0:1] op_sel:[0,1,0] op_sel_hi:[1,0,0]
	v_sub_f32_e32 v160, v162, v176
	v_mov_b32_e32 v164, v172
	v_mov_b32_e32 v165, v174
.LBB0_965:
	s_or_b64 exec, exec, s[0:1]
	v_mov_b32_e32 v162, v154
	v_mov_b32_e32 v163, v154
	v_pk_mul_f32 v[164:165], v[162:163], v[164:165]
	v_pk_mul_f32 v[160:161], v[154:155], v[160:161]
	v_pk_mul_f32 v[172:173], v[116:117], v[130:131]
	v_cvt_pk_bf16_f32 v160, v160, v161
	v_cvt_pk_bf16_f32 v161, v164, v165
	global_store_dwordx2 v[132:133], v[160:161], off offset:64
	global_load_dwordx4 v[158:161], v[158:159], off offset:192
	v_pk_mul_f32 v[164:165], v[114:115], v[130:131]
	s_waitcnt vmcnt(0)
	v_mov_b64_e32 v[236:237], v[158:159]
	v_mov_b64_e32 v[238:239], v[160:161]
	v_pk_mul_f32 v[130:131], v[164:165], v[158:159]
	v_pk_mul_f32 v[158:159], v[172:173], v[160:161]
	s_and_saveexec_b64 s[0:1], vcc
	s_cbranch_execz .LBB0_967
	global_load_dwordx4 v[172:175], v[140:141], off offset:64
	s_waitcnt vmcnt(0)
	v_pk_mul_f32 v[164:165], v[130:131], v[172:173] op_sel:[1,1] op_sel_hi:[1,0]
	v_mul_f32_e32 v0, v159, v175
	v_pk_mul_f32 v[160:161], v[130:131], v[172:173]
	v_pk_fma_f32 v[130:131], v[130:131], v[172:173], v[164:165] op_sel_hi:[0,1,1]
	v_pk_fma_f32 v[172:173], v[158:159], v[174:175], v[0:1] op_sel_hi:[1,1,0] neg_lo:[0,0,1] neg_hi:[0,0,1]
	v_mul_f32_e32 v0, v159, v174
	v_pk_fma_f32 v[174:175], v[158:159], v[174:175], v[0:1] op_sel:[0,1,0] op_sel_hi:[1,0,0]
	v_sub_f32_e32 v130, v160, v164
	v_mov_b32_e32 v158, v172
	v_mov_b32_e32 v159, v174

.LBB0_989:
	s_and_b64 vcc, exec, s[0:1]
	s_cbranch_vccz .LBB0_991
	s_and_b64 s[0:1], s[68:69], exec
	v_readlane_b32 s0, v254, 25
	v_readlane_b32 s6, v254, 29
	v_readlane_b32 s1, v254, 26
	v_readlane_b32 s7, v254, 30
	v_ashrrev_i32_e32 v157, 31, v156
	s_cselect_b32 s1, s1, s7
	s_cselect_b32 s0, s0, s6
	v_lshlrev_b64 v[130:131], 10, v[156:157]
	v_lshl_add_u64 v[130:131], s[0:1], 0, v[130:131]
	s_lshl_b32 s0, s25, 2
	s_mov_b32 s1, s35
	v_lshl_add_u64 v[132:133], v[130:131], 0, s[0:1]
	v_lshl_add_u64 v[130:131], s[36:37], 2, v[148:149]
	global_load_dwordx4 v[156:159], v[130:131], off offset:-1024
	v_mul_f32_e32 v0, 0xbfb8aa3b, v126
	v_exp_f32_e32 v0, v0
	s_waitcnt vmcnt(0)
	v_mov_b64_e32 v[224:225], v[156:157]
	v_mov_b64_e32 v[226:227], v[158:159]
	v_sub_f32_e32 v161, 1.0, v157
	v_add_f32_e32 v0, 1.0, v0
	v_rcp_f32_e32 v126, v0
	v_mul_f32_e32 v0, 0xbfb8aa3b, v127
	v_exp_f32_e32 v0, v0
	v_sub_f32_e32 v160, 1.0, v156
	v_sub_f32_e32 v163, 1.0, v159
	v_sub_f32_e32 v162, 1.0, v158
	v_add_f32_e32 v0, 1.0, v0
	v_rcp_f32_e32 v127, v0
	v_mul_f32_e32 v0, 0xbfb8aa3b, v128
	v_exp_f32_e32 v0, v0
	v_pk_fma_f32 v[156:157], v[126:127], v[160:161], v[156:157]
	v_add_f32_e32 v0, 1.0, v0
	v_rcp_f32_e32 v128, v0
	v_mul_f32_e32 v0, 0xbfb8aa3b, v129
	v_exp_f32_e32 v0, v0
	s_nop 0
	v_add_f32_e32 v0, 1.0, v0
	v_rcp_f32_e32 v129, v0
	v_lshlrev_b32_e32 v0, 2, v138
	v_lshl_add_u64 v[126:127], v[132:133], 0, v[0:1]
	v_mul_f32_e32 v0, 0xbfb8aa3b, v122
	v_pk_fma_f32 v[158:159], v[128:129], v[162:163], v[158:159]
	global_store_dwordx4 v[126:127], v[156:159], off
	global_load_dwordx4 v[156:159], v[130:131], off offset:-960
	v_exp_f32_e32 v0, v0
	s_waitcnt vmcnt(0)
	v_mov_b64_e32 v[228:229], v[156:157]
	v_mov_b64_e32 v[230:231], v[158:159]
	v_sub_f32_e32 v129, 1.0, v157
	v_add_f32_e32 v0, 1.0, v0
	v_rcp_f32_e32 v122, v0
	v_mul_f32_e32 v0, 0xbfb8aa3b, v123
	v_exp_f32_e32 v0, v0
	v_sub_f32_e32 v128, 1.0, v156
	v_sub_f32_e32 v133, 1.0, v159
	v_sub_f32_e32 v132, 1.0, v158
	v_add_f32_e32 v0, 1.0, v0
	v_rcp_f32_e32 v123, v0
	v_mul_f32_e32 v0, 0xbfb8aa3b, v124
	v_exp_f32_e32 v0, v0
	v_pk_fma_f32 v[122:123], v[122:123], v[128:129], v[156:157]
	v_add_f32_e32 v0, 1.0, v0
	v_rcp_f32_e32 v124, v0
	v_mul_f32_e32 v0, 0xbfb8aa3b, v125
	v_exp_f32_e32 v0, v0
	s_nop 0
	v_add_f32_e32 v0, 1.0, v0
	v_rcp_f32_e32 v125, v0
	v_mul_f32_e32 v0, 0xbfb8aa3b, v118
	v_exp_f32_e32 v0, v0
	v_pk_fma_f32 v[124:125], v[124:125], v[132:133], v[158:159]
	global_store_dwordx4 v[126:127], v[122:125], off offset:64
	global_load_dwordx4 v[122:125], v[130:131], off offset:-896
	v_add_f32_e32 v0, 1.0, v0
	v_rcp_f32_e32 v118, v0
	v_mul_f32_e32 v0, 0xbfb8aa3b, v119
	v_exp_f32_e32 v0, v0
	s_waitcnt vmcnt(0)
	v_mov_b64_e32 v[232:233], v[122:123]
	v_mov_b64_e32 v[234:235], v[124:125]
	v_sub_f32_e32 v129, 1.0, v123
	v_add_f32_e32 v0, 1.0, v0
	v_rcp_f32_e32 v119, v0
	v_mul_f32_e32 v0, 0xbfb8aa3b, v120
	v_exp_f32_e32 v0, v0
	v_sub_f32_e32 v128, 1.0, v122
	v_sub_f32_e32 v133, 1.0, v125
	v_sub_f32_e32 v132, 1.0, v124
	v_add_f32_e32 v0, 1.0, v0
	v_rcp_f32_e32 v120, v0
	v_mul_f32_e32 v0, 0xbfb8aa3b, v121
	v_exp_f32_e32 v0, v0
	v_pk_fma_f32 v[118:119], v[118:119], v[128:129], v[122:123]
	v_add_f32_e32 v0, 1.0, v0
	v_rcp_f32_e32 v121, v0
	v_mul_f32_e32 v0, 0xbfb8aa3b, v114
	v_exp_f32_e32 v0, v0
	v_pk_fma_f32 v[120:121], v[120:121], v[132:133], v[124:125]
	global_store_dwordx4 v[126:127], v[118:121], off offset:128
	global_load_dwordx4 v[118:121], v[130:131], off offset:-832
	v_add_f32_e32 v0, 1.0, v0
	v_rcp_f32_e32 v114, v0
	v_mul_f32_e32 v0, 0xbfb8aa3b, v115
	v_exp_f32_e32 v0, v0
	s_waitcnt vmcnt(0)
	v_mov_b64_e32 v[236:237], v[118:119]
	v_mov_b64_e32 v[238:239], v[120:121]
	v_sub_f32_e32 v123, 1.0, v119
	v_add_f32_e32 v0, 1.0, v0
	v_rcp_f32_e32 v115, v0
	v_mul_f32_e32 v0, 0xbfb8aa3b, v116
	v_exp_f32_e32 v0, v0
	v_sub_f32_e32 v122, 1.0, v118
	v_sub_f32_e32 v125, 1.0, v121
	v_sub_f32_e32 v124, 1.0, v120
	v_add_f32_e32 v0, 1.0, v0
	v_rcp_f32_e32 v116, v0
	v_mul_f32_e32 v0, 0xbfb8aa3b, v117
	v_exp_f32_e32 v0, v0
	v_pk_fma_f32 v[114:115], v[114:115], v[122:123], v[118:119]
	v_add_f32_e32 v0, 1.0, v0
	v_rcp_f32_e32 v117, v0
	s_nop 0
	v_pk_fma_f32 v[116:117], v[116:117], v[124:125], v[120:121]
	global_store_dwordx4 v[126:127], v[114:117], off offset:192

.LBB0_1006:
	s_and_b64 vcc, exec, s[0:1]
	s_cbranch_vccz .LBB0_1016
	v_mul_f32_e32 v0, v111, v111
	v_fmac_f32_e32 v0, v110, v110
	v_fmac_f32_e32 v0, v112, v112
	v_fmac_f32_e32 v0, v113, v113
	v_fmac_f32_e32 v0, v106, v106
	v_fmac_f32_e32 v0, v107, v107
	v_fmac_f32_e32 v0, v108, v108
	v_fmac_f32_e32 v0, v109, v109
	v_fmac_f32_e32 v0, v102, v102
	v_fmac_f32_e32 v0, v103, v103
	v_pk_mul_f32 v[114:115], v[104:105], v[104:105]
	v_pk_mul_f32 v[116:117], v[98:99], v[98:99]
	v_add_f32_e32 v0, v114, v0
	v_add_f32_e32 v0, v115, v0
	v_add_f32_e32 v0, v116, v0
	v_pk_mul_f32 v[114:115], v[100:101], v[100:101]
	v_add_f32_e32 v0, v117, v0
	v_add_f32_e32 v0, v114, v0
	v_add_f32_e32 v0, v115, v0
	v_and_b32_e32 v115, 64, v214
	v_xor_b32_e32 v114, 16, v214
	v_add_u32_e32 v115, 64, v115
	v_cmp_lt_i32_e32 vcc, v114, v115
	s_and_b64 s[0:1], s[42:43], exec
	s_cselect_b32 s1, s18, s20
	v_cndmask_b32_e32 v114, v214, v114, vcc
	v_lshlrev_b32_e32 v114, 2, v114
	ds_bpermute_b32 v114, v114, v0
	s_cselect_b32 s0, s17, s19
	s_lshr_b32 s4, s28, 2
	s_and_b32 s4, s4, 0x7f0
	s_waitcnt lgkmcnt(0)
	v_add_f32_e32 v0, v0, v114
	v_xor_b32_e32 v114, 32, v214
	v_cmp_lt_i32_e32 vcc, v114, v115
	v_or_b32_e32 v115, s4, v167
	v_lshlrev_b32_e32 v119, 3, v115
	v_cndmask_b32_e32 v114, v214, v114, vcc
	v_lshlrev_b32_e32 v114, 2, v114
	ds_bpermute_b32 v114, v114, v0
	v_cmp_gt_i32_e32 vcc, s81, v118
	s_waitcnt lgkmcnt(0)
	v_add_f32_e32 v0, v0, v114
	v_fmamk_f32 v0, v0, 0x3c800000, v208
	v_rsq_f32_e32 v114, v0
	v_lshlrev_b32_e32 v0, 2, v138
	s_nop 1
	v_mov_b64_e32 v[120:121], v[224:225]
	v_mov_b64_e32 v[122:123], v[226:227]
	v_pk_mul_f32 v[116:117], v[110:111], v[114:115] op_sel_hi:[1,0]
	v_pk_mul_f32 v[116:117], v[120:121], v[116:117]
	v_pk_mul_f32 v[120:121], v[112:113], v[114:115] op_sel_hi:[1,0]
	s_nop 0
	v_pk_mul_f32 v[124:125], v[122:123], v[120:121]
	s_and_saveexec_b64 s[4:5], vcc
	s_cbranch_execz .LBB0_1009
	v_readlane_b32 s6, v254, 6
	v_readlane_b32 s7, v254, 7
	s_nop 4
	global_load_dwordx4 v[120:123], v119, s[6:7]
	s_waitcnt vmcnt(0)
	v_pk_mul_f32 v[128:129], v[116:117], v[120:121] op_sel:[1,1] op_sel_hi:[1,0]
	v_pk_mul_f32 v[126:127], v[116:117], v[120:121]
	v_pk_fma_f32 v[116:117], v[116:117], v[120:121], v[128:129] op_sel_hi:[0,1,1]
	v_mul_f32_e32 v116, v125, v123
	v_pk_fma_f32 v[120:121], v[124:125], v[122:123], v[116:117] op_sel_hi:[1,1,0] neg_lo:[0,0,1] neg_hi:[0,0,1]
	v_mul_f32_e32 v116, v125, v122
	v_pk_fma_f32 v[122:123], v[124:125], v[122:123], v[116:117] op_sel:[0,1,0] op_sel_hi:[1,0,0]
	v_sub_f32_e32 v116, v126, v128
	v_mov_b32_e32 v124, v120
	v_mov_b32_e32 v125, v122
.LBB0_1009:
	s_or_b64 exec, exec, s[4:5]
	v_lshl_add_u64 v[120:121], s[0:1], 0, v[0:1]
	v_readlane_b32 s0, v254, 35
	v_readlane_b32 s1, v254, 36
	v_pk_mul_f32 v[128:129], v[154:155], v[116:117]
	v_lshlrev_b32_e32 v0, 1, v138
	v_mov_b64_e32 v[122:123], s[0:1]
	v_mad_i64_i32 v[122:123], s[0:1], v118, s52, v[122:123]
	s_lshl_b32 s0, s27, 1
	s_mov_b32 s1, s35
	v_lshl_add_u64 v[122:123], v[122:123], 0, s[0:1]
	v_lshl_add_u64 v[126:127], s[76:77], 1, v[122:123]
	v_mov_b32_e32 v122, v154
	v_mov_b32_e32 v123, v154
	v_pk_mul_f32 v[124:125], v[122:123], v[124:125]
	v_lshl_add_u64 v[116:117], v[126:127], 0, v[0:1]
	v_cvt_pk_bf16_f32 v126, v128, v129
	v_cvt_pk_bf16_f32 v127, v124, v125
	global_store_dwordx2 v[116:117], v[126:127], off
	s_nop 1
	v_mov_b64_e32 v[124:125], v[228:229]
	v_mov_b64_e32 v[126:127], v[230:231]
	v_mov_b32_e32 v115, v114
	v_pk_mul_f32 v[128:129], v[106:107], v[114:115]
	v_pk_mul_f32 v[124:125], v[128:129], v[124:125]
	v_pk_mul_f32 v[128:129], v[108:109], v[114:115]
	s_nop 0
	v_pk_mul_f32 v[126:127], v[128:129], v[126:127]
	s_and_saveexec_b64 s[0:1], vcc
	s_cbranch_execz .LBB0_1011
	v_readlane_b32 s4, v254, 6
	v_readlane_b32 s5, v254, 7
	s_nop 4
	global_load_dwordx4 v[128:131], v119, s[4:5] offset:64
	s_waitcnt vmcnt(0)
	v_pk_mul_f32 v[156:157], v[124:125], v[128:129] op_sel:[1,1] op_sel_hi:[1,0]
	v_mul_f32_e32 v0, v127, v131
	v_pk_mul_f32 v[132:133], v[124:125], v[128:129]
	v_pk_fma_f32 v[124:125], v[124:125], v[128:129], v[156:157] op_sel_hi:[0,1,1]
	v_pk_fma_f32 v[128:129], v[126:127], v[130:131], v[0:1] op_sel_hi:[1,1,0] neg_lo:[0,0,1] neg_hi:[0,0,1]
	v_mul_f32_e32 v0, v127, v130
	v_pk_fma_f32 v[130:131], v[126:127], v[130:131], v[0:1] op_sel:[0,1,0] op_sel_hi:[1,0,0]
	v_sub_f32_e32 v124, v132, v156
	v_mov_b32_e32 v126, v128
	v_mov_b32_e32 v127, v130
.LBB0_1011:
	s_or_b64 exec, exec, s[0:1]
	v_pk_mul_f32 v[122:123], v[122:123], v[126:127]
	v_pk_mul_f32 v[124:125], v[154:155], v[124:125]
	v_pk_mul_f32 v[126:127], v[102:103], v[114:115]
	v_cvt_pk_bf16_f32 v124, v124, v125
	v_cvt_pk_bf16_f32 v125, v122, v123
	global_store_dwordx2 v[116:117], v[124:125], off offset:32
	s_nop 1
	v_mov_b64_e32 v[122:123], v[232:233]
	v_mov_b64_e32 v[124:125], v[234:235]
	v_pk_mul_f32 v[122:123], v[126:127], v[122:123]
	v_pk_mul_f32 v[126:127], v[104:105], v[114:115]
	s_nop 0
	v_pk_mul_f32 v[126:127], v[126:127], v[124:125]
	s_and_saveexec_b64 s[0:1], vcc
	s_cbranch_execz .LBB0_1013
	global_load_dwordx4 v[128:131], v[142:143], off
	s_waitcnt vmcnt(0)
	v_pk_mul_f32 v[132:133], v[122:123], v[128:129] op_sel:[1,1] op_sel_hi:[1,0]
	v_mul_f32_e32 v0, v127, v131
	v_pk_mul_f32 v[124:125], v[122:123], v[128:129]
	v_pk_fma_f32 v[122:123], v[122:123], v[128:129], v[132:133] op_sel_hi:[0,1,1]
	v_pk_fma_f32 v[128:129], v[126:127], v[130:131], v[0:1] op_sel_hi:[1,1,0] neg_lo:[0,0,1] neg_hi:[0,0,1]
	v_mul_f32_e32 v0, v127, v130
	v_pk_fma_f32 v[130:131], v[126:127], v[130:131], v[0:1] op_sel:[0,1,0] op_sel_hi:[1,0,0]
	v_sub_f32_e32 v122, v124, v132
	v_mov_b32_e32 v126, v128
	v_mov_b32_e32 v127, v130
.LBB0_1013:
	s_or_b64 exec, exec, s[0:1]
	v_mov_b32_e32 v124, v154
	v_mov_b32_e32 v125, v154
	v_pk_mul_f32 v[126:127], v[124:125], v[126:127]
	v_pk_mul_f32 v[122:123], v[154:155], v[122:123]
	v_pk_mul_f32 v[128:129], v[100:101], v[114:115]
	v_cvt_pk_bf16_f32 v122, v122, v123
	v_cvt_pk_bf16_f32 v123, v126, v127
	global_store_dwordx2 v[116:117], v[122:123], off offset:64
	s_nop 1
	v_mov_b64_e32 v[120:121], v[236:237]
	v_mov_b64_e32 v[122:123], v[238:239]
	v_pk_mul_f32 v[126:127], v[98:99], v[114:115]
	v_pk_mul_f32 v[114:115], v[126:127], v[120:121]
	v_pk_mul_f32 v[120:121], v[128:129], v[122:123]
	s_and_saveexec_b64 s[0:1], vcc
	s_cbranch_execz .LBB0_1015
	global_load_dwordx4 v[126:129], v[142:143], off offset:64
	s_waitcnt vmcnt(0)
	v_pk_mul_f32 v[130:131], v[114:115], v[126:127] op_sel:[1,1] op_sel_hi:[1,0]
	v_mul_f32_e32 v0, v121, v129
	v_pk_mul_f32 v[122:123], v[114:115], v[126:127]
	v_pk_fma_f32 v[114:115], v[114:115], v[126:127], v[130:131] op_sel_hi:[0,1,1]
	v_pk_fma_f32 v[126:127], v[120:121], v[128:129], v[0:1] op_sel_hi:[1,1,0] neg_lo:[0,0,1] neg_hi:[0,0,1]
	v_mul_f32_e32 v0, v121, v128
	v_pk_fma_f32 v[128:129], v[120:121], v[128:129], v[0:1] op_sel:[0,1,0] op_sel_hi:[1,0,0]
	v_sub_f32_e32 v114, v122, v130
	v_mov_b32_e32 v120, v126
	v_mov_b32_e32 v121, v128

.LBB0_1037:
	s_and_b64 vcc, exec, s[0:1]
	s_cbranch_vccz .LBB0_1039
	s_and_b64 s[0:1], s[68:69], exec
	v_readlane_b32 s0, v254, 25
	v_readlane_b32 s4, v254, 29
	v_readlane_b32 s1, v254, 26
	v_readlane_b32 s5, v254, 30
	v_ashrrev_i32_e32 v119, 31, v118
	s_cselect_b32 s1, s1, s5
	s_cselect_b32 s0, s0, s4
	v_lshlrev_b64 v[114:115], 10, v[118:119]
	v_lshl_add_u64 v[114:115], s[0:1], 0, v[114:115]
	s_lshl_b32 s0, s25, 2
	s_mov_b32 s1, s35
	v_lshl_add_u64 v[120:121], v[114:115], 0, s[0:1]
	v_lshl_add_u64 v[114:115], s[36:37], 2, v[148:149]
	s_nop 1
	v_mov_b64_e32 v[116:117], v[224:225]
	v_mov_b64_e32 v[118:119], v[226:227]
	v_mul_f32_e32 v0, 0xbfb8aa3b, v110
	v_exp_f32_e32 v0, v0
	v_sub_f32_e32 v123, 1.0, v117
	v_add_f32_e32 v0, 1.0, v0
	v_rcp_f32_e32 v110, v0
	v_mul_f32_e32 v0, 0xbfb8aa3b, v111
	v_exp_f32_e32 v0, v0
	v_sub_f32_e32 v122, 1.0, v116
	v_sub_f32_e32 v125, 1.0, v119
	v_sub_f32_e32 v124, 1.0, v118
	v_add_f32_e32 v0, 1.0, v0
	v_rcp_f32_e32 v111, v0
	v_mul_f32_e32 v0, 0xbfb8aa3b, v112
	v_exp_f32_e32 v0, v0
	v_pk_fma_f32 v[116:117], v[110:111], v[122:123], v[116:117]
	v_add_f32_e32 v0, 1.0, v0
	v_rcp_f32_e32 v112, v0
	v_mul_f32_e32 v0, 0xbfb8aa3b, v113
	v_exp_f32_e32 v0, v0
	s_nop 0
	v_add_f32_e32 v0, 1.0, v0
	v_rcp_f32_e32 v113, v0
	v_lshlrev_b32_e32 v0, 2, v138
	v_lshl_add_u64 v[110:111], v[120:121], 0, v[0:1]
	v_mul_f32_e32 v0, 0xbfb8aa3b, v106
	v_pk_fma_f32 v[118:119], v[112:113], v[124:125], v[118:119]
	global_store_dwordx4 v[110:111], v[116:119], off
	s_nop 1
	v_mov_b64_e32 v[116:117], v[228:229]
	v_mov_b64_e32 v[118:119], v[230:231]
	v_exp_f32_e32 v0, v0
	v_sub_f32_e32 v113, 1.0, v117
	v_add_f32_e32 v0, 1.0, v0
	v_rcp_f32_e32 v106, v0
	v_mul_f32_e32 v0, 0xbfb8aa3b, v107
	v_exp_f32_e32 v0, v0
	v_sub_f32_e32 v112, 1.0, v116
	v_sub_f32_e32 v121, 1.0, v119
	v_sub_f32_e32 v120, 1.0, v118
	v_add_f32_e32 v0, 1.0, v0
	v_rcp_f32_e32 v107, v0
	v_mul_f32_e32 v0, 0xbfb8aa3b, v108
	v_exp_f32_e32 v0, v0
	v_pk_fma_f32 v[106:107], v[106:107], v[112:113], v[116:117]
	v_add_f32_e32 v0, 1.0, v0
	v_rcp_f32_e32 v108, v0
	v_mul_f32_e32 v0, 0xbfb8aa3b, v109
	v_exp_f32_e32 v0, v0
	s_nop 0
	v_add_f32_e32 v0, 1.0, v0
	v_rcp_f32_e32 v109, v0
	v_mul_f32_e32 v0, 0xbfb8aa3b, v102
	v_exp_f32_e32 v0, v0
	v_pk_fma_f32 v[108:109], v[108:109], v[120:121], v[118:119]
	global_store_dwordx4 v[110:111], v[106:109], off offset:64
	s_nop 1
	v_mov_b64_e32 v[106:107], v[232:233]
	v_mov_b64_e32 v[108:109], v[234:235]
	v_add_f32_e32 v0, 1.0, v0
	v_rcp_f32_e32 v102, v0
	v_mul_f32_e32 v0, 0xbfb8aa3b, v103
	v_exp_f32_e32 v0, v0
	v_sub_f32_e32 v113, 1.0, v107
	v_add_f32_e32 v0, 1.0, v0
	v_rcp_f32_e32 v103, v0
	v_mul_f32_e32 v0, 0xbfb8aa3b, v104
	v_exp_f32_e32 v0, v0
	v_sub_f32_e32 v112, 1.0, v106
	v_sub_f32_e32 v117, 1.0, v109
	v_sub_f32_e32 v116, 1.0, v108
	v_add_f32_e32 v0, 1.0, v0
	v_rcp_f32_e32 v104, v0
	v_mul_f32_e32 v0, 0xbfb8aa3b, v105
	v_exp_f32_e32 v0, v0
	v_pk_fma_f32 v[102:103], v[102:103], v[112:113], v[106:107]
	v_add_f32_e32 v0, 1.0, v0
	v_rcp_f32_e32 v105, v0
	v_mul_f32_e32 v0, 0xbfb8aa3b, v98
	v_exp_f32_e32 v0, v0
	v_pk_fma_f32 v[104:105], v[104:105], v[116:117], v[108:109]
	global_store_dwordx4 v[110:111], v[102:105], off offset:128
	s_nop 1
	v_mov_b64_e32 v[102:103], v[236:237]
	v_mov_b64_e32 v[104:105], v[238:239]
	v_add_f32_e32 v0, 1.0, v0
	v_rcp_f32_e32 v98, v0
	v_mul_f32_e32 v0, 0xbfb8aa3b, v99
	v_exp_f32_e32 v0, v0
	v_sub_f32_e32 v107, 1.0, v103
	v_add_f32_e32 v0, 1.0, v0
	v_rcp_f32_e32 v99, v0
	v_mul_f32_e32 v0, 0xbfb8aa3b, v100
	v_exp_f32_e32 v0, v0
	v_sub_f32_e32 v106, 1.0, v102
	v_sub_f32_e32 v109, 1.0, v105
	v_sub_f32_e32 v108, 1.0, v104
	v_add_f32_e32 v0, 1.0, v0
	v_rcp_f32_e32 v100, v0
	v_mul_f32_e32 v0, 0xbfb8aa3b, v101
	v_exp_f32_e32 v0, v0
	v_pk_fma_f32 v[98:99], v[98:99], v[106:107], v[102:103]
	v_add_f32_e32 v0, 1.0, v0
	v_rcp_f32_e32 v101, v0
	s_nop 0
	v_pk_fma_f32 v[100:101], v[100:101], v[108:109], v[104:105]
	global_store_dwordx4 v[110:111], v[98:101], off offset:192

.LBB0_1054:
	s_and_b64 vcc, exec, s[0:1]
	s_cbranch_vccz .LBB0_1064
	v_mul_f32_e32 v0, v95, v95
	v_fmac_f32_e32 v0, v94, v94
	v_fmac_f32_e32 v0, v96, v96
	v_fmac_f32_e32 v0, v97, v97
	v_fmac_f32_e32 v0, v90, v90
	v_fmac_f32_e32 v0, v91, v91
	v_fmac_f32_e32 v0, v92, v92
	v_fmac_f32_e32 v0, v93, v93
	v_fmac_f32_e32 v0, v86, v86
	v_fmac_f32_e32 v0, v87, v87
	v_pk_mul_f32 v[98:99], v[88:89], v[88:89]
	v_pk_mul_f32 v[100:101], v[82:83], v[82:83]
	v_add_f32_e32 v0, v98, v0
	v_add_f32_e32 v0, v99, v0
	v_add_f32_e32 v0, v100, v0
	v_pk_mul_f32 v[98:99], v[84:85], v[84:85]
	v_add_f32_e32 v0, v101, v0
	v_add_f32_e32 v0, v98, v0
	v_add_f32_e32 v0, v99, v0
	v_and_b32_e32 v99, 64, v214
	v_xor_b32_e32 v98, 16, v214
	v_add_u32_e32 v99, 64, v99
	v_cmp_lt_i32_e32 vcc, v98, v99
	s_and_b64 s[0:1], s[42:43], exec
	s_cselect_b32 s1, s18, s20
	v_cndmask_b32_e32 v98, v214, v98, vcc
	v_lshlrev_b32_e32 v98, 2, v98
	ds_bpermute_b32 v98, v98, v0
	s_cselect_b32 s0, s17, s19
	s_lshr_b32 s4, s28, 2
	s_and_b32 s4, s4, 0x7f0
	s_waitcnt lgkmcnt(0)
	v_add_f32_e32 v0, v0, v98
	v_xor_b32_e32 v98, 32, v214
	v_cmp_lt_i32_e32 vcc, v98, v99
	v_or_b32_e32 v99, s4, v167
	v_lshlrev_b32_e32 v103, 3, v99
	v_cndmask_b32_e32 v98, v214, v98, vcc
	v_lshlrev_b32_e32 v98, 2, v98
	ds_bpermute_b32 v98, v98, v0
	v_cmp_gt_i32_e32 vcc, s81, v102
	s_waitcnt lgkmcnt(0)
	v_add_f32_e32 v0, v0, v98
	v_fmamk_f32 v0, v0, 0x3c800000, v208
	v_rsq_f32_e32 v98, v0
	v_lshlrev_b32_e32 v0, 2, v138
	s_nop 1
	v_mov_b64_e32 v[104:105], v[224:225]
	v_mov_b64_e32 v[106:107], v[226:227]
	v_pk_mul_f32 v[100:101], v[94:95], v[98:99] op_sel_hi:[1,0]
	v_pk_mul_f32 v[100:101], v[104:105], v[100:101]
	v_pk_mul_f32 v[104:105], v[96:97], v[98:99] op_sel_hi:[1,0]
	s_nop 0
	v_pk_mul_f32 v[108:109], v[106:107], v[104:105]
	s_and_saveexec_b64 s[4:5], vcc
	s_cbranch_execz .LBB0_1057
	v_readlane_b32 s6, v254, 6
	v_readlane_b32 s7, v254, 7
	s_nop 4
	global_load_dwordx4 v[104:107], v103, s[6:7]
	s_waitcnt vmcnt(0)
	v_pk_mul_f32 v[112:113], v[100:101], v[104:105] op_sel:[1,1] op_sel_hi:[1,0]
	v_pk_mul_f32 v[110:111], v[100:101], v[104:105]
	v_pk_fma_f32 v[100:101], v[100:101], v[104:105], v[112:113] op_sel_hi:[0,1,1]
	v_mul_f32_e32 v100, v109, v107
	v_pk_fma_f32 v[104:105], v[108:109], v[106:107], v[100:101] op_sel_hi:[1,1,0] neg_lo:[0,0,1] neg_hi:[0,0,1]
	v_mul_f32_e32 v100, v109, v106
	v_pk_fma_f32 v[106:107], v[108:109], v[106:107], v[100:101] op_sel:[0,1,0] op_sel_hi:[1,0,0]
	v_sub_f32_e32 v100, v110, v112
	v_mov_b32_e32 v108, v104
	v_mov_b32_e32 v109, v106
.LBB0_1057:
	s_or_b64 exec, exec, s[4:5]
	v_lshl_add_u64 v[104:105], s[0:1], 0, v[0:1]
	v_readlane_b32 s0, v254, 35
	v_readlane_b32 s1, v254, 36
	v_pk_mul_f32 v[112:113], v[154:155], v[100:101]
	v_lshlrev_b32_e32 v0, 1, v138
	v_mov_b64_e32 v[106:107], s[0:1]
	v_mad_i64_i32 v[106:107], s[0:1], v102, s52, v[106:107]
	s_lshl_b32 s0, s27, 1
	s_mov_b32 s1, s35
	v_lshl_add_u64 v[106:107], v[106:107], 0, s[0:1]
	v_lshl_add_u64 v[110:111], s[76:77], 1, v[106:107]
	v_mov_b32_e32 v106, v154
	v_mov_b32_e32 v107, v154
	v_pk_mul_f32 v[108:109], v[106:107], v[108:109]
	v_lshl_add_u64 v[100:101], v[110:111], 0, v[0:1]
	v_cvt_pk_bf16_f32 v110, v112, v113
	v_cvt_pk_bf16_f32 v111, v108, v109
	global_store_dwordx2 v[100:101], v[110:111], off
	s_nop 1
	v_mov_b64_e32 v[108:109], v[228:229]
	v_mov_b64_e32 v[110:111], v[230:231]
	v_mov_b32_e32 v99, v98
	v_pk_mul_f32 v[112:113], v[90:91], v[98:99]
	v_pk_mul_f32 v[108:109], v[112:113], v[108:109]
	v_pk_mul_f32 v[112:113], v[92:93], v[98:99]
	s_nop 0
	v_pk_mul_f32 v[110:111], v[112:113], v[110:111]
	s_and_saveexec_b64 s[0:1], vcc
	s_cbranch_execz .LBB0_1059
	v_readlane_b32 s4, v254, 6
	v_readlane_b32 s5, v254, 7
	s_nop 4
	global_load_dwordx4 v[112:115], v103, s[4:5] offset:64
	s_waitcnt vmcnt(0)
	v_pk_mul_f32 v[118:119], v[108:109], v[112:113] op_sel:[1,1] op_sel_hi:[1,0]
	v_mul_f32_e32 v0, v111, v115
	v_pk_mul_f32 v[116:117], v[108:109], v[112:113]
	v_pk_fma_f32 v[108:109], v[108:109], v[112:113], v[118:119] op_sel_hi:[0,1,1]
	v_pk_fma_f32 v[112:113], v[110:111], v[114:115], v[0:1] op_sel_hi:[1,1,0] neg_lo:[0,0,1] neg_hi:[0,0,1]
	v_mul_f32_e32 v0, v111, v114
	v_pk_fma_f32 v[114:115], v[110:111], v[114:115], v[0:1] op_sel:[0,1,0] op_sel_hi:[1,0,0]
	v_sub_f32_e32 v108, v116, v118
	v_mov_b32_e32 v110, v112
	v_mov_b32_e32 v111, v114
.LBB0_1059:
	s_or_b64 exec, exec, s[0:1]
	v_pk_mul_f32 v[106:107], v[106:107], v[110:111]
	v_pk_mul_f32 v[108:109], v[154:155], v[108:109]
	v_pk_mul_f32 v[110:111], v[86:87], v[98:99]
	v_cvt_pk_bf16_f32 v108, v108, v109
	v_cvt_pk_bf16_f32 v109, v106, v107
	global_store_dwordx2 v[100:101], v[108:109], off offset:32
	s_nop 1
	v_mov_b64_e32 v[106:107], v[232:233]
	v_mov_b64_e32 v[108:109], v[234:235]
	v_pk_mul_f32 v[106:107], v[110:111], v[106:107]
	v_pk_mul_f32 v[110:111], v[88:89], v[98:99]
	s_nop 0
	v_pk_mul_f32 v[110:111], v[110:111], v[108:109]
	s_and_saveexec_b64 s[0:1], vcc
	s_cbranch_execz .LBB0_1061
	global_load_dwordx4 v[112:115], v[144:145], off
	s_waitcnt vmcnt(0)
	v_pk_mul_f32 v[116:117], v[106:107], v[112:113] op_sel:[1,1] op_sel_hi:[1,0]
	v_mul_f32_e32 v0, v111, v115
	v_pk_mul_f32 v[108:109], v[106:107], v[112:113]
	v_pk_fma_f32 v[106:107], v[106:107], v[112:113], v[116:117] op_sel_hi:[0,1,1]
	v_pk_fma_f32 v[112:113], v[110:111], v[114:115], v[0:1] op_sel_hi:[1,1,0] neg_lo:[0,0,1] neg_hi:[0,0,1]
	v_mul_f32_e32 v0, v111, v114
	v_pk_fma_f32 v[114:115], v[110:111], v[114:115], v[0:1] op_sel:[0,1,0] op_sel_hi:[1,0,0]
	v_sub_f32_e32 v106, v108, v116
	v_mov_b32_e32 v110, v112
	v_mov_b32_e32 v111, v114
.LBB0_1061:
	s_or_b64 exec, exec, s[0:1]
	v_mov_b32_e32 v108, v154
	v_mov_b32_e32 v109, v154
	v_pk_mul_f32 v[110:111], v[108:109], v[110:111]
	v_pk_mul_f32 v[106:107], v[154:155], v[106:107]
	v_pk_mul_f32 v[112:113], v[84:85], v[98:99]
	v_cvt_pk_bf16_f32 v106, v106, v107
	v_cvt_pk_bf16_f32 v107, v110, v111
	global_store_dwordx2 v[100:101], v[106:107], off offset:64
	s_nop 1
	v_mov_b64_e32 v[104:105], v[236:237]
	v_mov_b64_e32 v[106:107], v[238:239]
	v_pk_mul_f32 v[110:111], v[82:83], v[98:99]
	v_pk_mul_f32 v[98:99], v[110:111], v[104:105]
	v_pk_mul_f32 v[104:105], v[112:113], v[106:107]
	s_and_saveexec_b64 s[0:1], vcc
	s_cbranch_execz .LBB0_1063
	global_load_dwordx4 v[110:113], v[144:145], off offset:64
	s_waitcnt vmcnt(0)
	v_pk_mul_f32 v[114:115], v[98:99], v[110:111] op_sel:[1,1] op_sel_hi:[1,0]
	v_mul_f32_e32 v0, v105, v113
	v_pk_mul_f32 v[106:107], v[98:99], v[110:111]
	v_pk_fma_f32 v[98:99], v[98:99], v[110:111], v[114:115] op_sel_hi:[0,1,1]
	v_pk_fma_f32 v[110:111], v[104:105], v[112:113], v[0:1] op_sel_hi:[1,1,0] neg_lo:[0,0,1] neg_hi:[0,0,1]
	v_mul_f32_e32 v0, v105, v112
	v_pk_fma_f32 v[112:113], v[104:105], v[112:113], v[0:1] op_sel:[0,1,0] op_sel_hi:[1,0,0]
	v_sub_f32_e32 v98, v106, v114
	v_mov_b32_e32 v104, v110
	v_mov_b32_e32 v105, v112

.LBB0_1085:
	s_and_b64 vcc, exec, s[0:1]
	s_cbranch_vccz .LBB0_1087
	s_and_b64 s[0:1], s[68:69], exec
	v_readlane_b32 s0, v254, 25
	v_readlane_b32 s4, v254, 29
	v_readlane_b32 s1, v254, 26
	v_readlane_b32 s5, v254, 30
	v_ashrrev_i32_e32 v103, 31, v102
	s_cselect_b32 s1, s1, s5
	s_cselect_b32 s0, s0, s4
	v_lshlrev_b64 v[98:99], 10, v[102:103]
	v_lshl_add_u64 v[98:99], s[0:1], 0, v[98:99]
	s_lshl_b32 s0, s25, 2
	s_mov_b32 s1, s35
	v_lshl_add_u64 v[104:105], v[98:99], 0, s[0:1]
	v_lshl_add_u64 v[98:99], s[36:37], 2, v[148:149]
	s_nop 1
	v_mov_b64_e32 v[100:101], v[224:225]
	v_mov_b64_e32 v[102:103], v[226:227]
	v_mul_f32_e32 v0, 0xbfb8aa3b, v94
	v_exp_f32_e32 v0, v0
	v_sub_f32_e32 v107, 1.0, v101
	v_add_f32_e32 v0, 1.0, v0
	v_rcp_f32_e32 v94, v0
	v_mul_f32_e32 v0, 0xbfb8aa3b, v95
	v_exp_f32_e32 v0, v0
	v_sub_f32_e32 v106, 1.0, v100
	v_sub_f32_e32 v109, 1.0, v103
	v_sub_f32_e32 v108, 1.0, v102
	v_add_f32_e32 v0, 1.0, v0
	v_rcp_f32_e32 v95, v0
	v_mul_f32_e32 v0, 0xbfb8aa3b, v96
	v_exp_f32_e32 v0, v0
	v_pk_fma_f32 v[100:101], v[94:95], v[106:107], v[100:101]
	v_add_f32_e32 v0, 1.0, v0
	v_rcp_f32_e32 v96, v0
	v_mul_f32_e32 v0, 0xbfb8aa3b, v97
	v_exp_f32_e32 v0, v0
	s_nop 0
	v_add_f32_e32 v0, 1.0, v0
	v_rcp_f32_e32 v97, v0
	v_lshlrev_b32_e32 v0, 2, v138
	v_lshl_add_u64 v[94:95], v[104:105], 0, v[0:1]
	v_mul_f32_e32 v0, 0xbfb8aa3b, v90
	v_pk_fma_f32 v[102:103], v[96:97], v[108:109], v[102:103]
	global_store_dwordx4 v[94:95], v[100:103], off
	s_nop 1
	v_mov_b64_e32 v[100:101], v[228:229]
	v_mov_b64_e32 v[102:103], v[230:231]
	v_exp_f32_e32 v0, v0
	v_sub_f32_e32 v97, 1.0, v101
	v_add_f32_e32 v0, 1.0, v0
	v_rcp_f32_e32 v90, v0
	v_mul_f32_e32 v0, 0xbfb8aa3b, v91
	v_exp_f32_e32 v0, v0
	v_sub_f32_e32 v96, 1.0, v100
	v_sub_f32_e32 v105, 1.0, v103
	v_sub_f32_e32 v104, 1.0, v102
	v_add_f32_e32 v0, 1.0, v0
	v_rcp_f32_e32 v91, v0
	v_mul_f32_e32 v0, 0xbfb8aa3b, v92
	v_exp_f32_e32 v0, v0
	v_pk_fma_f32 v[90:91], v[90:91], v[96:97], v[100:101]
	v_add_f32_e32 v0, 1.0, v0
	v_rcp_f32_e32 v92, v0
	v_mul_f32_e32 v0, 0xbfb8aa3b, v93
	v_exp_f32_e32 v0, v0
	s_nop 0
	v_add_f32_e32 v0, 1.0, v0
	v_rcp_f32_e32 v93, v0
	v_mul_f32_e32 v0, 0xbfb8aa3b, v86
	v_exp_f32_e32 v0, v0
	v_pk_fma_f32 v[92:93], v[92:93], v[104:105], v[102:103]
	global_store_dwordx4 v[94:95], v[90:93], off offset:64
	s_nop 1
	v_mov_b64_e32 v[90:91], v[232:233]
	v_mov_b64_e32 v[92:93], v[234:235]
	v_add_f32_e32 v0, 1.0, v0
	v_rcp_f32_e32 v86, v0
	v_mul_f32_e32 v0, 0xbfb8aa3b, v87
	v_exp_f32_e32 v0, v0
	v_sub_f32_e32 v97, 1.0, v91
	v_add_f32_e32 v0, 1.0, v0
	v_rcp_f32_e32 v87, v0
	v_mul_f32_e32 v0, 0xbfb8aa3b, v88
	v_exp_f32_e32 v0, v0
	v_sub_f32_e32 v96, 1.0, v90
	v_sub_f32_e32 v101, 1.0, v93
	v_sub_f32_e32 v100, 1.0, v92
	v_add_f32_e32 v0, 1.0, v0
	v_rcp_f32_e32 v88, v0
	v_mul_f32_e32 v0, 0xbfb8aa3b, v89
	v_exp_f32_e32 v0, v0
	v_pk_fma_f32 v[86:87], v[86:87], v[96:97], v[90:91]
	v_add_f32_e32 v0, 1.0, v0
	v_rcp_f32_e32 v89, v0
	v_mul_f32_e32 v0, 0xbfb8aa3b, v82
	v_exp_f32_e32 v0, v0
	v_pk_fma_f32 v[88:89], v[88:89], v[100:101], v[92:93]
	global_store_dwordx4 v[94:95], v[86:89], off offset:128
	s_nop 1
	v_mov_b64_e32 v[86:87], v[236:237]
	v_mov_b64_e32 v[88:89], v[238:239]
	v_add_f32_e32 v0, 1.0, v0
	v_rcp_f32_e32 v82, v0
	v_mul_f32_e32 v0, 0xbfb8aa3b, v83
	v_exp_f32_e32 v0, v0
	v_sub_f32_e32 v91, 1.0, v87
	v_add_f32_e32 v0, 1.0, v0
	v_rcp_f32_e32 v83, v0
	v_mul_f32_e32 v0, 0xbfb8aa3b, v84
	v_exp_f32_e32 v0, v0
	v_sub_f32_e32 v90, 1.0, v86
	v_sub_f32_e32 v93, 1.0, v89
	v_sub_f32_e32 v92, 1.0, v88
	v_add_f32_e32 v0, 1.0, v0
	v_rcp_f32_e32 v84, v0
	v_mul_f32_e32 v0, 0xbfb8aa3b, v85
	v_exp_f32_e32 v0, v0
	v_pk_fma_f32 v[82:83], v[82:83], v[90:91], v[86:87]
	v_add_f32_e32 v0, 1.0, v0
	v_rcp_f32_e32 v85, v0
	s_nop 0
	v_pk_fma_f32 v[84:85], v[84:85], v[92:93], v[88:89]
	global_store_dwordx4 v[94:95], v[82:85], off offset:192

.LBB0_1102:
	s_and_b64 vcc, exec, s[0:1]
	s_cbranch_vccz .LBB0_1112
	v_mul_f32_e32 v0, v79, v79
	v_fmac_f32_e32 v0, v78, v78
	v_fmac_f32_e32 v0, v80, v80
	v_fmac_f32_e32 v0, v81, v81
	v_fmac_f32_e32 v0, v74, v74
	v_fmac_f32_e32 v0, v75, v75
	v_fmac_f32_e32 v0, v76, v76
	v_fmac_f32_e32 v0, v77, v77
	v_fmac_f32_e32 v0, v70, v70
	v_fmac_f32_e32 v0, v71, v71
	v_pk_mul_f32 v[82:83], v[72:73], v[72:73]
	v_pk_mul_f32 v[84:85], v[66:67], v[66:67]
	v_add_f32_e32 v0, v82, v0
	v_add_f32_e32 v0, v83, v0
	v_add_f32_e32 v0, v84, v0
	v_pk_mul_f32 v[82:83], v[68:69], v[68:69]
	v_add_f32_e32 v0, v85, v0
	v_add_f32_e32 v0, v82, v0
	v_add_f32_e32 v0, v83, v0
	v_and_b32_e32 v83, 64, v214
	v_xor_b32_e32 v82, 16, v214
	v_add_u32_e32 v83, 64, v83
	v_cmp_lt_i32_e32 vcc, v82, v83
	s_and_b64 s[0:1], s[42:43], exec
	s_cselect_b32 s1, s18, s20
	v_cndmask_b32_e32 v82, v214, v82, vcc
	v_lshlrev_b32_e32 v82, 2, v82
	ds_bpermute_b32 v82, v82, v0
	s_cselect_b32 s0, s17, s19
	s_lshr_b32 s4, s28, 2
	s_and_b32 s4, s4, 0x7f0
	s_waitcnt lgkmcnt(0)
	v_add_f32_e32 v0, v0, v82
	v_xor_b32_e32 v82, 32, v214
	v_cmp_lt_i32_e32 vcc, v82, v83
	v_or_b32_e32 v83, s4, v167
	v_lshlrev_b32_e32 v87, 3, v83
	v_cndmask_b32_e32 v82, v214, v82, vcc
	v_lshlrev_b32_e32 v82, 2, v82
	ds_bpermute_b32 v82, v82, v0
	v_cmp_gt_i32_e32 vcc, s81, v86
	s_waitcnt lgkmcnt(0)
	v_add_f32_e32 v0, v0, v82
	v_fmamk_f32 v0, v0, 0x3c800000, v208
	v_rsq_f32_e32 v82, v0
	v_lshlrev_b32_e32 v0, 2, v138
	s_nop 1
	v_mov_b64_e32 v[88:89], v[224:225]
	v_mov_b64_e32 v[90:91], v[226:227]
	v_pk_mul_f32 v[84:85], v[78:79], v[82:83] op_sel_hi:[1,0]
	v_pk_mul_f32 v[84:85], v[88:89], v[84:85]
	v_pk_mul_f32 v[88:89], v[80:81], v[82:83] op_sel_hi:[1,0]
	s_nop 0
	v_pk_mul_f32 v[92:93], v[90:91], v[88:89]
	s_and_saveexec_b64 s[4:5], vcc
	s_cbranch_execz .LBB0_1105
	v_readlane_b32 s6, v254, 6
	v_readlane_b32 s7, v254, 7
	s_nop 4
	global_load_dwordx4 v[88:91], v87, s[6:7]
	s_waitcnt vmcnt(0)
	v_pk_mul_f32 v[96:97], v[84:85], v[88:89] op_sel:[1,1] op_sel_hi:[1,0]
	v_pk_mul_f32 v[94:95], v[84:85], v[88:89]
	v_pk_fma_f32 v[84:85], v[84:85], v[88:89], v[96:97] op_sel_hi:[0,1,1]
	v_mul_f32_e32 v84, v93, v91
	v_pk_fma_f32 v[88:89], v[92:93], v[90:91], v[84:85] op_sel_hi:[1,1,0] neg_lo:[0,0,1] neg_hi:[0,0,1]
	v_mul_f32_e32 v84, v93, v90
	v_pk_fma_f32 v[90:91], v[92:93], v[90:91], v[84:85] op_sel:[0,1,0] op_sel_hi:[1,0,0]
	v_sub_f32_e32 v84, v94, v96
	v_mov_b32_e32 v92, v88
	v_mov_b32_e32 v93, v90
.LBB0_1105:
	s_or_b64 exec, exec, s[4:5]
	v_lshl_add_u64 v[88:89], s[0:1], 0, v[0:1]
	v_readlane_b32 s0, v254, 35
	v_readlane_b32 s1, v254, 36
	v_pk_mul_f32 v[96:97], v[154:155], v[84:85]
	v_lshlrev_b32_e32 v0, 1, v138
	v_mov_b64_e32 v[90:91], s[0:1]
	v_mad_i64_i32 v[90:91], s[0:1], v86, s52, v[90:91]
	s_lshl_b32 s0, s27, 1
	s_mov_b32 s1, s35
	v_lshl_add_u64 v[90:91], v[90:91], 0, s[0:1]
	v_lshl_add_u64 v[94:95], s[76:77], 1, v[90:91]
	v_mov_b32_e32 v90, v154
	v_mov_b32_e32 v91, v154
	v_pk_mul_f32 v[92:93], v[90:91], v[92:93]
	v_lshl_add_u64 v[84:85], v[94:95], 0, v[0:1]
	v_cvt_pk_bf16_f32 v94, v96, v97
	v_cvt_pk_bf16_f32 v95, v92, v93
	global_store_dwordx2 v[84:85], v[94:95], off
	s_nop 1
	v_mov_b64_e32 v[92:93], v[228:229]
	v_mov_b64_e32 v[94:95], v[230:231]
	v_mov_b32_e32 v83, v82
	v_pk_mul_f32 v[96:97], v[74:75], v[82:83]
	v_pk_mul_f32 v[92:93], v[96:97], v[92:93]
	v_pk_mul_f32 v[96:97], v[76:77], v[82:83]
	s_nop 0
	v_pk_mul_f32 v[94:95], v[96:97], v[94:95]
	s_and_saveexec_b64 s[0:1], vcc
	s_cbranch_execz .LBB0_1107
	v_readlane_b32 s4, v254, 6
	v_readlane_b32 s5, v254, 7
	s_nop 4
	global_load_dwordx4 v[96:99], v87, s[4:5] offset:64
	s_waitcnt vmcnt(0)
	v_pk_mul_f32 v[102:103], v[92:93], v[96:97] op_sel:[1,1] op_sel_hi:[1,0]
	v_mul_f32_e32 v0, v95, v99
	v_pk_mul_f32 v[100:101], v[92:93], v[96:97]
	v_pk_fma_f32 v[92:93], v[92:93], v[96:97], v[102:103] op_sel_hi:[0,1,1]
	v_pk_fma_f32 v[96:97], v[94:95], v[98:99], v[0:1] op_sel_hi:[1,1,0] neg_lo:[0,0,1] neg_hi:[0,0,1]
	v_mul_f32_e32 v0, v95, v98
	v_pk_fma_f32 v[98:99], v[94:95], v[98:99], v[0:1] op_sel:[0,1,0] op_sel_hi:[1,0,0]
	v_sub_f32_e32 v92, v100, v102
	v_mov_b32_e32 v94, v96
	v_mov_b32_e32 v95, v98
.LBB0_1107:
	s_or_b64 exec, exec, s[0:1]
	v_pk_mul_f32 v[90:91], v[90:91], v[94:95]
	v_pk_mul_f32 v[92:93], v[154:155], v[92:93]
	v_pk_mul_f32 v[94:95], v[70:71], v[82:83]
	v_cvt_pk_bf16_f32 v92, v92, v93
	v_cvt_pk_bf16_f32 v93, v90, v91
	global_store_dwordx2 v[84:85], v[92:93], off offset:32
	s_nop 1
	v_mov_b64_e32 v[90:91], v[232:233]
	v_mov_b64_e32 v[92:93], v[234:235]
	v_pk_mul_f32 v[90:91], v[94:95], v[90:91]
	v_pk_mul_f32 v[94:95], v[72:73], v[82:83]
	s_nop 0
	v_pk_mul_f32 v[94:95], v[94:95], v[92:93]
	s_and_saveexec_b64 s[0:1], vcc
	s_cbranch_execz .LBB0_1109
	global_load_dwordx4 v[96:99], v[146:147], off
	s_waitcnt vmcnt(0)
	v_pk_mul_f32 v[100:101], v[90:91], v[96:97] op_sel:[1,1] op_sel_hi:[1,0]
	v_mul_f32_e32 v0, v95, v99
	v_pk_mul_f32 v[92:93], v[90:91], v[96:97]
	v_pk_fma_f32 v[90:91], v[90:91], v[96:97], v[100:101] op_sel_hi:[0,1,1]
	v_pk_fma_f32 v[96:97], v[94:95], v[98:99], v[0:1] op_sel_hi:[1,1,0] neg_lo:[0,0,1] neg_hi:[0,0,1]
	v_mul_f32_e32 v0, v95, v98
	v_pk_fma_f32 v[98:99], v[94:95], v[98:99], v[0:1] op_sel:[0,1,0] op_sel_hi:[1,0,0]
	v_sub_f32_e32 v90, v92, v100
	v_mov_b32_e32 v94, v96
	v_mov_b32_e32 v95, v98
.LBB0_1109:
	s_or_b64 exec, exec, s[0:1]
	v_mov_b32_e32 v92, v154
	v_mov_b32_e32 v93, v154
	v_pk_mul_f32 v[94:95], v[92:93], v[94:95]
	v_pk_mul_f32 v[90:91], v[154:155], v[90:91]
	v_pk_mul_f32 v[96:97], v[68:69], v[82:83]
	v_cvt_pk_bf16_f32 v90, v90, v91
	v_cvt_pk_bf16_f32 v91, v94, v95
	global_store_dwordx2 v[84:85], v[90:91], off offset:64
	s_nop 1
	v_mov_b64_e32 v[88:89], v[236:237]
	v_mov_b64_e32 v[90:91], v[238:239]
	v_pk_mul_f32 v[94:95], v[66:67], v[82:83]
	v_pk_mul_f32 v[82:83], v[94:95], v[88:89]
	v_pk_mul_f32 v[88:89], v[96:97], v[90:91]
	s_and_saveexec_b64 s[0:1], vcc
	s_cbranch_execz .LBB0_1111
	global_load_dwordx4 v[94:97], v[146:147], off offset:64
	s_waitcnt vmcnt(0)
	v_pk_mul_f32 v[98:99], v[82:83], v[94:95] op_sel:[1,1] op_sel_hi:[1,0]
	v_mul_f32_e32 v0, v89, v97
	v_pk_mul_f32 v[90:91], v[82:83], v[94:95]
	v_pk_fma_f32 v[82:83], v[82:83], v[94:95], v[98:99] op_sel_hi:[0,1,1]
	v_pk_fma_f32 v[94:95], v[88:89], v[96:97], v[0:1] op_sel_hi:[1,1,0] neg_lo:[0,0,1] neg_hi:[0,0,1]
	v_mul_f32_e32 v0, v89, v96
	v_pk_fma_f32 v[96:97], v[88:89], v[96:97], v[0:1] op_sel:[0,1,0] op_sel_hi:[1,0,0]
	v_sub_f32_e32 v82, v90, v98
	v_mov_b32_e32 v88, v94
	v_mov_b32_e32 v89, v96

.LBB0_1133:
	s_and_b64 vcc, exec, s[0:1]
	s_cbranch_vccz .LBB0_1135
	s_and_b64 s[0:1], s[68:69], exec
	v_readlane_b32 s0, v254, 25
	v_readlane_b32 s4, v254, 29
	v_readlane_b32 s1, v254, 26
	v_readlane_b32 s5, v254, 30
	v_ashrrev_i32_e32 v87, 31, v86
	s_cselect_b32 s1, s1, s5
	s_cselect_b32 s0, s0, s4
	v_lshlrev_b64 v[82:83], 10, v[86:87]
	v_lshl_add_u64 v[82:83], s[0:1], 0, v[82:83]
	s_lshl_b32 s0, s25, 2
	s_mov_b32 s1, s35
	v_lshl_add_u64 v[88:89], v[82:83], 0, s[0:1]
	v_lshl_add_u64 v[82:83], s[36:37], 2, v[148:149]
	s_nop 1
	v_mov_b64_e32 v[84:85], v[224:225]
	v_mov_b64_e32 v[86:87], v[226:227]
	v_mul_f32_e32 v0, 0xbfb8aa3b, v78
	v_exp_f32_e32 v0, v0
	v_sub_f32_e32 v91, 1.0, v85
	v_add_f32_e32 v0, 1.0, v0
	v_rcp_f32_e32 v78, v0
	v_mul_f32_e32 v0, 0xbfb8aa3b, v79
	v_exp_f32_e32 v0, v0
	v_sub_f32_e32 v90, 1.0, v84
	v_sub_f32_e32 v93, 1.0, v87
	v_sub_f32_e32 v92, 1.0, v86
	v_add_f32_e32 v0, 1.0, v0
	v_rcp_f32_e32 v79, v0
	v_mul_f32_e32 v0, 0xbfb8aa3b, v80
	v_exp_f32_e32 v0, v0
	v_pk_fma_f32 v[84:85], v[78:79], v[90:91], v[84:85]
	v_add_f32_e32 v0, 1.0, v0
	v_rcp_f32_e32 v80, v0
	v_mul_f32_e32 v0, 0xbfb8aa3b, v81
	v_exp_f32_e32 v0, v0
	s_nop 0
	v_add_f32_e32 v0, 1.0, v0
	v_rcp_f32_e32 v81, v0
	v_lshlrev_b32_e32 v0, 2, v138
	v_lshl_add_u64 v[78:79], v[88:89], 0, v[0:1]
	v_mul_f32_e32 v0, 0xbfb8aa3b, v74
	v_pk_fma_f32 v[86:87], v[80:81], v[92:93], v[86:87]
	global_store_dwordx4 v[78:79], v[84:87], off
	s_nop 1
	v_mov_b64_e32 v[84:85], v[228:229]
	v_mov_b64_e32 v[86:87], v[230:231]
	v_exp_f32_e32 v0, v0
	v_sub_f32_e32 v81, 1.0, v85
	v_add_f32_e32 v0, 1.0, v0
	v_rcp_f32_e32 v74, v0
	v_mul_f32_e32 v0, 0xbfb8aa3b, v75
	v_exp_f32_e32 v0, v0
	v_sub_f32_e32 v80, 1.0, v84
	v_sub_f32_e32 v89, 1.0, v87
	v_sub_f32_e32 v88, 1.0, v86
	v_add_f32_e32 v0, 1.0, v0
	v_rcp_f32_e32 v75, v0
	v_mul_f32_e32 v0, 0xbfb8aa3b, v76
	v_exp_f32_e32 v0, v0
	v_pk_fma_f32 v[74:75], v[74:75], v[80:81], v[84:85]
	v_add_f32_e32 v0, 1.0, v0
	v_rcp_f32_e32 v76, v0
	v_mul_f32_e32 v0, 0xbfb8aa3b, v77
	v_exp_f32_e32 v0, v0
	s_nop 0
	v_add_f32_e32 v0, 1.0, v0
	v_rcp_f32_e32 v77, v0
	v_mul_f32_e32 v0, 0xbfb8aa3b, v70
	v_exp_f32_e32 v0, v0
	v_pk_fma_f32 v[76:77], v[76:77], v[88:89], v[86:87]
	global_store_dwordx4 v[78:79], v[74:77], off offset:64
	s_nop 1
	v_mov_b64_e32 v[74:75], v[232:233]
	v_mov_b64_e32 v[76:77], v[234:235]
	v_add_f32_e32 v0, 1.0, v0
	v_rcp_f32_e32 v70, v0
	v_mul_f32_e32 v0, 0xbfb8aa3b, v71
	v_exp_f32_e32 v0, v0
	v_sub_f32_e32 v81, 1.0, v75
	v_add_f32_e32 v0, 1.0, v0
	v_rcp_f32_e32 v71, v0
	v_mul_f32_e32 v0, 0xbfb8aa3b, v72
	v_exp_f32_e32 v0, v0
	v_sub_f32_e32 v80, 1.0, v74
	v_sub_f32_e32 v85, 1.0, v77
	v_sub_f32_e32 v84, 1.0, v76
	v_add_f32_e32 v0, 1.0, v0
	v_rcp_f32_e32 v72, v0
	v_mul_f32_e32 v0, 0xbfb8aa3b, v73
	v_exp_f32_e32 v0, v0
	v_pk_fma_f32 v[70:71], v[70:71], v[80:81], v[74:75]
	v_add_f32_e32 v0, 1.0, v0
	v_rcp_f32_e32 v73, v0
	v_mul_f32_e32 v0, 0xbfb8aa3b, v66
	v_exp_f32_e32 v0, v0
	v_pk_fma_f32 v[72:73], v[72:73], v[84:85], v[76:77]
	global_store_dwordx4 v[78:79], v[70:73], off offset:128
	s_nop 1
	v_mov_b64_e32 v[70:71], v[236:237]
	v_mov_b64_e32 v[72:73], v[238:239]
	v_add_f32_e32 v0, 1.0, v0
	v_rcp_f32_e32 v66, v0
	v_mul_f32_e32 v0, 0xbfb8aa3b, v67
	v_exp_f32_e32 v0, v0
	v_sub_f32_e32 v75, 1.0, v71
	v_add_f32_e32 v0, 1.0, v0
	v_rcp_f32_e32 v67, v0
	v_mul_f32_e32 v0, 0xbfb8aa3b, v68
	v_exp_f32_e32 v0, v0
	v_sub_f32_e32 v74, 1.0, v70
	v_sub_f32_e32 v77, 1.0, v73
	v_sub_f32_e32 v76, 1.0, v72
	v_add_f32_e32 v0, 1.0, v0
	v_rcp_f32_e32 v68, v0
	v_mul_f32_e32 v0, 0xbfb8aa3b, v69
	v_exp_f32_e32 v0, v0
	v_pk_fma_f32 v[66:67], v[66:67], v[74:75], v[70:71]
	v_add_f32_e32 v0, 1.0, v0
	v_rcp_f32_e32 v69, v0
	s_nop 0
	v_pk_fma_f32 v[68:69], v[68:69], v[76:77], v[72:73]
	global_store_dwordx4 v[78:79], v[66:69], off offset:192

.LBB0_1150:
	s_and_b64 vcc, exec, s[0:1]
	s_cbranch_vccz .LBB0_1160
	v_mul_f32_e32 v0, v63, v63
	v_fmac_f32_e32 v0, v62, v62
	v_fmac_f32_e32 v0, v64, v64
	v_fmac_f32_e32 v0, v65, v65
	v_fmac_f32_e32 v0, v58, v58
	v_fmac_f32_e32 v0, v59, v59
	v_fmac_f32_e32 v0, v60, v60
	v_fmac_f32_e32 v0, v61, v61
	v_fmac_f32_e32 v0, v54, v54
	v_fmac_f32_e32 v0, v55, v55
	v_pk_mul_f32 v[66:67], v[56:57], v[56:57]
	v_pk_mul_f32 v[68:69], v[50:51], v[50:51]
	v_add_f32_e32 v0, v66, v0
	v_add_f32_e32 v0, v67, v0
	v_add_f32_e32 v0, v68, v0
	v_pk_mul_f32 v[66:67], v[52:53], v[52:53]
	v_add_f32_e32 v0, v69, v0
	v_add_f32_e32 v0, v66, v0
	v_add_f32_e32 v0, v67, v0
	v_and_b32_e32 v67, 64, v214
	v_xor_b32_e32 v66, 16, v214
	v_add_u32_e32 v67, 64, v67
	v_cmp_lt_i32_e32 vcc, v66, v67
	s_and_b64 s[0:1], s[42:43], exec
	s_cselect_b32 s1, s18, s20
	v_cndmask_b32_e32 v66, v214, v66, vcc
	v_lshlrev_b32_e32 v66, 2, v66
	ds_bpermute_b32 v66, v66, v0
	s_cselect_b32 s0, s17, s19
	s_lshr_b32 s4, s28, 2
	s_and_b32 s4, s4, 0x7f0
	s_waitcnt lgkmcnt(0)
	v_add_f32_e32 v0, v0, v66
	v_xor_b32_e32 v66, 32, v214
	v_cmp_lt_i32_e32 vcc, v66, v67
	v_or_b32_e32 v67, s4, v167
	v_lshlrev_b32_e32 v71, 3, v67
	v_cndmask_b32_e32 v66, v214, v66, vcc
	v_lshlrev_b32_e32 v66, 2, v66
	ds_bpermute_b32 v66, v66, v0
	v_cmp_gt_i32_e32 vcc, s81, v70
	s_waitcnt lgkmcnt(0)
	v_add_f32_e32 v0, v0, v66
	v_fmamk_f32 v0, v0, 0x3c800000, v208
	v_rsq_f32_e32 v66, v0
	v_lshlrev_b32_e32 v0, 2, v138
	s_nop 1
	v_mov_b64_e32 v[72:73], v[224:225]
	v_mov_b64_e32 v[74:75], v[226:227]
	v_pk_mul_f32 v[68:69], v[62:63], v[66:67] op_sel_hi:[1,0]
	v_pk_mul_f32 v[68:69], v[72:73], v[68:69]
	v_pk_mul_f32 v[72:73], v[64:65], v[66:67] op_sel_hi:[1,0]
	s_nop 0
	v_pk_mul_f32 v[76:77], v[74:75], v[72:73]
	s_and_saveexec_b64 s[4:5], vcc
	s_cbranch_execz .LBB0_1153
	v_readlane_b32 s6, v254, 6
	v_readlane_b32 s7, v254, 7
	s_nop 4
	global_load_dwordx4 v[72:75], v71, s[6:7]
	s_waitcnt vmcnt(0)
	v_pk_mul_f32 v[80:81], v[68:69], v[72:73] op_sel:[1,1] op_sel_hi:[1,0]
	v_pk_mul_f32 v[78:79], v[68:69], v[72:73]
	v_pk_fma_f32 v[68:69], v[68:69], v[72:73], v[80:81] op_sel_hi:[0,1,1]
	v_mul_f32_e32 v68, v77, v75
	v_pk_fma_f32 v[72:73], v[76:77], v[74:75], v[68:69] op_sel_hi:[1,1,0] neg_lo:[0,0,1] neg_hi:[0,0,1]
	v_mul_f32_e32 v68, v77, v74
	v_pk_fma_f32 v[74:75], v[76:77], v[74:75], v[68:69] op_sel:[0,1,0] op_sel_hi:[1,0,0]
	v_sub_f32_e32 v68, v78, v80
	v_mov_b32_e32 v76, v72
	v_mov_b32_e32 v77, v74
.LBB0_1153:
	s_or_b64 exec, exec, s[4:5]
	v_lshl_add_u64 v[72:73], s[0:1], 0, v[0:1]
	v_readlane_b32 s0, v254, 35
	v_readlane_b32 s1, v254, 36
	v_pk_mul_f32 v[80:81], v[154:155], v[68:69]
	v_lshlrev_b32_e32 v0, 1, v138
	v_mov_b64_e32 v[74:75], s[0:1]
	v_mad_i64_i32 v[74:75], s[0:1], v70, s52, v[74:75]
	s_lshl_b32 s0, s27, 1
	s_mov_b32 s1, s35
	v_lshl_add_u64 v[74:75], v[74:75], 0, s[0:1]
	v_lshl_add_u64 v[78:79], s[76:77], 1, v[74:75]
	v_mov_b32_e32 v74, v154
	v_mov_b32_e32 v75, v154
	v_pk_mul_f32 v[76:77], v[74:75], v[76:77]
	v_lshl_add_u64 v[68:69], v[78:79], 0, v[0:1]
	v_cvt_pk_bf16_f32 v78, v80, v81
	v_cvt_pk_bf16_f32 v79, v76, v77
	global_store_dwordx2 v[68:69], v[78:79], off
	s_nop 1
	v_mov_b64_e32 v[76:77], v[228:229]
	v_mov_b64_e32 v[78:79], v[230:231]
	v_mov_b32_e32 v67, v66
	v_pk_mul_f32 v[80:81], v[58:59], v[66:67]
	v_pk_mul_f32 v[76:77], v[80:81], v[76:77]
	v_pk_mul_f32 v[80:81], v[60:61], v[66:67]
	s_nop 0
	v_pk_mul_f32 v[78:79], v[80:81], v[78:79]
	s_and_saveexec_b64 s[0:1], vcc
	s_cbranch_execz .LBB0_1155
	v_readlane_b32 s4, v254, 6
	v_readlane_b32 s5, v254, 7
	s_nop 4
	global_load_dwordx4 v[80:83], v71, s[4:5] offset:64
	s_waitcnt vmcnt(0)
	v_pk_mul_f32 v[86:87], v[76:77], v[80:81] op_sel:[1,1] op_sel_hi:[1,0]
	v_mul_f32_e32 v0, v79, v83
	v_pk_mul_f32 v[84:85], v[76:77], v[80:81]
	v_pk_fma_f32 v[76:77], v[76:77], v[80:81], v[86:87] op_sel_hi:[0,1,1]
	v_pk_fma_f32 v[80:81], v[78:79], v[82:83], v[0:1] op_sel_hi:[1,1,0] neg_lo:[0,0,1] neg_hi:[0,0,1]
	v_mul_f32_e32 v0, v79, v82
	v_pk_fma_f32 v[82:83], v[78:79], v[82:83], v[0:1] op_sel:[0,1,0] op_sel_hi:[1,0,0]
	v_sub_f32_e32 v76, v84, v86
	v_mov_b32_e32 v78, v80
	v_mov_b32_e32 v79, v82
.LBB0_1155:
	s_or_b64 exec, exec, s[0:1]
	v_pk_mul_f32 v[74:75], v[74:75], v[78:79]
	v_pk_mul_f32 v[76:77], v[154:155], v[76:77]
	v_pk_mul_f32 v[78:79], v[54:55], v[66:67]
	v_cvt_pk_bf16_f32 v76, v76, v77
	v_cvt_pk_bf16_f32 v77, v74, v75
	global_store_dwordx2 v[68:69], v[76:77], off offset:32
	s_nop 1
	v_mov_b64_e32 v[74:75], v[232:233]
	v_mov_b64_e32 v[76:77], v[234:235]
	v_pk_mul_f32 v[74:75], v[78:79], v[74:75]
	v_pk_mul_f32 v[78:79], v[56:57], v[66:67]
	s_nop 0
	v_pk_mul_f32 v[78:79], v[78:79], v[76:77]
	s_and_saveexec_b64 s[0:1], vcc
	s_cbranch_execz .LBB0_1157
	global_load_dwordx4 v[80:83], v[140:141], off
	s_waitcnt vmcnt(0)
	v_pk_mul_f32 v[84:85], v[74:75], v[80:81] op_sel:[1,1] op_sel_hi:[1,0]
	v_mul_f32_e32 v0, v79, v83
	v_pk_mul_f32 v[76:77], v[74:75], v[80:81]
	v_pk_fma_f32 v[74:75], v[74:75], v[80:81], v[84:85] op_sel_hi:[0,1,1]
	v_pk_fma_f32 v[80:81], v[78:79], v[82:83], v[0:1] op_sel_hi:[1,1,0] neg_lo:[0,0,1] neg_hi:[0,0,1]
	v_mul_f32_e32 v0, v79, v82
	v_pk_fma_f32 v[82:83], v[78:79], v[82:83], v[0:1] op_sel:[0,1,0] op_sel_hi:[1,0,0]
	v_sub_f32_e32 v74, v76, v84
	v_mov_b32_e32 v78, v80
	v_mov_b32_e32 v79, v82
.LBB0_1157:
	s_or_b64 exec, exec, s[0:1]
	v_mov_b32_e32 v76, v154
	v_mov_b32_e32 v77, v154
	v_pk_mul_f32 v[78:79], v[76:77], v[78:79]
	v_pk_mul_f32 v[74:75], v[154:155], v[74:75]
	v_pk_mul_f32 v[80:81], v[52:53], v[66:67]
	v_cvt_pk_bf16_f32 v74, v74, v75
	v_cvt_pk_bf16_f32 v75, v78, v79
	global_store_dwordx2 v[68:69], v[74:75], off offset:64
	s_nop 1
	v_mov_b64_e32 v[72:73], v[236:237]
	v_mov_b64_e32 v[74:75], v[238:239]
	v_pk_mul_f32 v[78:79], v[50:51], v[66:67]
	v_pk_mul_f32 v[66:67], v[78:79], v[72:73]
	v_pk_mul_f32 v[72:73], v[80:81], v[74:75]
	s_and_saveexec_b64 s[0:1], vcc
	s_cbranch_execz .LBB0_1159
	global_load_dwordx4 v[78:81], v[140:141], off offset:64
	s_waitcnt vmcnt(0)
	v_pk_mul_f32 v[82:83], v[66:67], v[78:79] op_sel:[1,1] op_sel_hi:[1,0]
	v_mul_f32_e32 v0, v73, v81
	v_pk_mul_f32 v[74:75], v[66:67], v[78:79]
	v_pk_fma_f32 v[66:67], v[66:67], v[78:79], v[82:83] op_sel_hi:[0,1,1]
	v_pk_fma_f32 v[78:79], v[72:73], v[80:81], v[0:1] op_sel_hi:[1,1,0] neg_lo:[0,0,1] neg_hi:[0,0,1]
	v_mul_f32_e32 v0, v73, v80
	v_pk_fma_f32 v[80:81], v[72:73], v[80:81], v[0:1] op_sel:[0,1,0] op_sel_hi:[1,0,0]
	v_sub_f32_e32 v66, v74, v82
	v_mov_b32_e32 v72, v78
	v_mov_b32_e32 v73, v80

.LBB0_1181:
	s_and_b64 vcc, exec, s[0:1]
	s_cbranch_vccz .LBB0_1183
	s_and_b64 s[0:1], s[68:69], exec
	v_readlane_b32 s0, v254, 25
	v_readlane_b32 s4, v254, 29
	v_readlane_b32 s1, v254, 26
	v_readlane_b32 s5, v254, 30
	v_ashrrev_i32_e32 v71, 31, v70
	s_cselect_b32 s1, s1, s5
	s_cselect_b32 s0, s0, s4
	v_lshlrev_b64 v[66:67], 10, v[70:71]
	v_lshl_add_u64 v[66:67], s[0:1], 0, v[66:67]
	s_lshl_b32 s0, s25, 2
	s_mov_b32 s1, s35
	v_lshl_add_u64 v[72:73], v[66:67], 0, s[0:1]
	v_lshl_add_u64 v[66:67], s[36:37], 2, v[148:149]
	s_nop 1
	v_mov_b64_e32 v[68:69], v[224:225]
	v_mov_b64_e32 v[70:71], v[226:227]
	v_mul_f32_e32 v0, 0xbfb8aa3b, v62
	v_exp_f32_e32 v0, v0
	v_sub_f32_e32 v75, 1.0, v69
	v_add_f32_e32 v0, 1.0, v0
	v_rcp_f32_e32 v62, v0
	v_mul_f32_e32 v0, 0xbfb8aa3b, v63
	v_exp_f32_e32 v0, v0
	v_sub_f32_e32 v74, 1.0, v68
	v_sub_f32_e32 v77, 1.0, v71
	v_sub_f32_e32 v76, 1.0, v70
	v_add_f32_e32 v0, 1.0, v0
	v_rcp_f32_e32 v63, v0
	v_mul_f32_e32 v0, 0xbfb8aa3b, v64
	v_exp_f32_e32 v0, v0
	v_pk_fma_f32 v[68:69], v[62:63], v[74:75], v[68:69]
	v_add_f32_e32 v0, 1.0, v0
	v_rcp_f32_e32 v64, v0
	v_mul_f32_e32 v0, 0xbfb8aa3b, v65
	v_exp_f32_e32 v0, v0
	s_nop 0
	v_add_f32_e32 v0, 1.0, v0
	v_rcp_f32_e32 v65, v0
	v_lshlrev_b32_e32 v0, 2, v138
	v_lshl_add_u64 v[62:63], v[72:73], 0, v[0:1]
	v_mul_f32_e32 v0, 0xbfb8aa3b, v58
	v_pk_fma_f32 v[70:71], v[64:65], v[76:77], v[70:71]
	global_store_dwordx4 v[62:63], v[68:71], off
	s_nop 1
	v_mov_b64_e32 v[68:69], v[228:229]
	v_mov_b64_e32 v[70:71], v[230:231]
	v_exp_f32_e32 v0, v0
	v_sub_f32_e32 v65, 1.0, v69
	v_add_f32_e32 v0, 1.0, v0
	v_rcp_f32_e32 v58, v0
	v_mul_f32_e32 v0, 0xbfb8aa3b, v59
	v_exp_f32_e32 v0, v0
	v_sub_f32_e32 v64, 1.0, v68
	v_sub_f32_e32 v73, 1.0, v71
	v_sub_f32_e32 v72, 1.0, v70
	v_add_f32_e32 v0, 1.0, v0
	v_rcp_f32_e32 v59, v0
	v_mul_f32_e32 v0, 0xbfb8aa3b, v60
	v_exp_f32_e32 v0, v0
	v_pk_fma_f32 v[58:59], v[58:59], v[64:65], v[68:69]
	v_add_f32_e32 v0, 1.0, v0
	v_rcp_f32_e32 v60, v0
	v_mul_f32_e32 v0, 0xbfb8aa3b, v61
	v_exp_f32_e32 v0, v0
	s_nop 0
	v_add_f32_e32 v0, 1.0, v0
	v_rcp_f32_e32 v61, v0
	v_mul_f32_e32 v0, 0xbfb8aa3b, v54
	v_exp_f32_e32 v0, v0
	v_pk_fma_f32 v[60:61], v[60:61], v[72:73], v[70:71]
	global_store_dwordx4 v[62:63], v[58:61], off offset:64
	s_nop 1
	v_mov_b64_e32 v[58:59], v[232:233]
	v_mov_b64_e32 v[60:61], v[234:235]
	v_add_f32_e32 v0, 1.0, v0
	v_rcp_f32_e32 v54, v0
	v_mul_f32_e32 v0, 0xbfb8aa3b, v55
	v_exp_f32_e32 v0, v0
	v_sub_f32_e32 v65, 1.0, v59
	v_add_f32_e32 v0, 1.0, v0
	v_rcp_f32_e32 v55, v0
	v_mul_f32_e32 v0, 0xbfb8aa3b, v56
	v_exp_f32_e32 v0, v0
	v_sub_f32_e32 v64, 1.0, v58
	v_sub_f32_e32 v69, 1.0, v61
	v_sub_f32_e32 v68, 1.0, v60
	v_add_f32_e32 v0, 1.0, v0
	v_rcp_f32_e32 v56, v0
	v_mul_f32_e32 v0, 0xbfb8aa3b, v57
	v_exp_f32_e32 v0, v0
	v_pk_fma_f32 v[54:55], v[54:55], v[64:65], v[58:59]
	v_add_f32_e32 v0, 1.0, v0
	v_rcp_f32_e32 v57, v0
	v_mul_f32_e32 v0, 0xbfb8aa3b, v50
	v_exp_f32_e32 v0, v0
	v_pk_fma_f32 v[56:57], v[56:57], v[68:69], v[60:61]
	global_store_dwordx4 v[62:63], v[54:57], off offset:128
	s_nop 1
	v_mov_b64_e32 v[54:55], v[236:237]
	v_mov_b64_e32 v[56:57], v[238:239]
	v_add_f32_e32 v0, 1.0, v0
	v_rcp_f32_e32 v50, v0
	v_mul_f32_e32 v0, 0xbfb8aa3b, v51
	v_exp_f32_e32 v0, v0
	v_sub_f32_e32 v59, 1.0, v55
	v_add_f32_e32 v0, 1.0, v0
	v_rcp_f32_e32 v51, v0
	v_mul_f32_e32 v0, 0xbfb8aa3b, v52
	v_exp_f32_e32 v0, v0
	v_sub_f32_e32 v58, 1.0, v54
	v_sub_f32_e32 v61, 1.0, v57
	v_sub_f32_e32 v60, 1.0, v56
	v_add_f32_e32 v0, 1.0, v0
	v_rcp_f32_e32 v52, v0
	v_mul_f32_e32 v0, 0xbfb8aa3b, v53
	v_exp_f32_e32 v0, v0
	v_pk_fma_f32 v[50:51], v[50:51], v[58:59], v[54:55]
	v_add_f32_e32 v0, 1.0, v0
	v_rcp_f32_e32 v53, v0
	s_nop 0
	v_pk_fma_f32 v[52:53], v[52:53], v[60:61], v[56:57]
	global_store_dwordx4 v[62:63], v[50:53], off offset:192

.LBB0_1198:
	s_and_b64 vcc, exec, s[0:1]
	s_cbranch_vccz .LBB0_1208
	v_mul_f32_e32 v0, v47, v47
	v_fmac_f32_e32 v0, v46, v46
	v_fmac_f32_e32 v0, v48, v48
	v_fmac_f32_e32 v0, v49, v49
	v_fmac_f32_e32 v0, v42, v42
	v_fmac_f32_e32 v0, v43, v43
	v_fmac_f32_e32 v0, v44, v44
	v_fmac_f32_e32 v0, v45, v45
	v_fmac_f32_e32 v0, v38, v38
	v_fmac_f32_e32 v0, v39, v39
	v_pk_mul_f32 v[50:51], v[40:41], v[40:41]
	v_pk_mul_f32 v[52:53], v[34:35], v[34:35]
	v_add_f32_e32 v0, v50, v0
	v_add_f32_e32 v0, v51, v0
	v_add_f32_e32 v0, v52, v0
	v_pk_mul_f32 v[50:51], v[36:37], v[36:37]
	v_add_f32_e32 v0, v53, v0
	v_add_f32_e32 v0, v50, v0
	v_add_f32_e32 v0, v51, v0
	v_and_b32_e32 v51, 64, v214
	v_xor_b32_e32 v50, 16, v214
	v_add_u32_e32 v51, 64, v51
	v_cmp_lt_i32_e32 vcc, v50, v51
	s_and_b64 s[0:1], s[42:43], exec
	s_cselect_b32 s1, s18, s20
	v_cndmask_b32_e32 v50, v214, v50, vcc
	v_lshlrev_b32_e32 v50, 2, v50
	ds_bpermute_b32 v50, v50, v0
	s_cselect_b32 s0, s17, s19
	s_lshr_b32 s4, s28, 2
	s_and_b32 s4, s4, 0x7f0
	s_waitcnt lgkmcnt(0)
	v_add_f32_e32 v0, v0, v50
	v_xor_b32_e32 v50, 32, v214
	v_cmp_lt_i32_e32 vcc, v50, v51
	v_or_b32_e32 v51, s4, v167
	v_lshlrev_b32_e32 v55, 3, v51
	v_cndmask_b32_e32 v50, v214, v50, vcc
	v_lshlrev_b32_e32 v50, 2, v50
	ds_bpermute_b32 v50, v50, v0
	v_cmp_gt_i32_e32 vcc, s81, v54
	s_waitcnt lgkmcnt(0)
	v_add_f32_e32 v0, v0, v50
	v_fmamk_f32 v0, v0, 0x3c800000, v208
	v_rsq_f32_e32 v50, v0
	v_lshlrev_b32_e32 v0, 2, v138
	s_nop 1
	v_mov_b64_e32 v[56:57], v[224:225]
	v_mov_b64_e32 v[58:59], v[226:227]
	v_pk_mul_f32 v[52:53], v[46:47], v[50:51] op_sel_hi:[1,0]
	v_pk_mul_f32 v[52:53], v[56:57], v[52:53]
	v_pk_mul_f32 v[56:57], v[48:49], v[50:51] op_sel_hi:[1,0]
	s_nop 0
	v_pk_mul_f32 v[60:61], v[58:59], v[56:57]
	s_and_saveexec_b64 s[4:5], vcc
	s_cbranch_execz .LBB0_1201
	v_readlane_b32 s6, v254, 6
	v_readlane_b32 s7, v254, 7
	s_nop 4
	global_load_dwordx4 v[56:59], v55, s[6:7]
	s_waitcnt vmcnt(0)
	v_pk_mul_f32 v[64:65], v[52:53], v[56:57] op_sel:[1,1] op_sel_hi:[1,0]
	v_pk_mul_f32 v[62:63], v[52:53], v[56:57]
	v_pk_fma_f32 v[52:53], v[52:53], v[56:57], v[64:65] op_sel_hi:[0,1,1]
	v_mul_f32_e32 v52, v61, v59
	v_pk_fma_f32 v[56:57], v[60:61], v[58:59], v[52:53] op_sel_hi:[1,1,0] neg_lo:[0,0,1] neg_hi:[0,0,1]
	v_mul_f32_e32 v52, v61, v58
	v_pk_fma_f32 v[58:59], v[60:61], v[58:59], v[52:53] op_sel:[0,1,0] op_sel_hi:[1,0,0]
	v_sub_f32_e32 v52, v62, v64
	v_mov_b32_e32 v60, v56
	v_mov_b32_e32 v61, v58
.LBB0_1201:
	s_or_b64 exec, exec, s[4:5]
	v_lshl_add_u64 v[56:57], s[0:1], 0, v[0:1]
	v_readlane_b32 s0, v254, 35
	v_readlane_b32 s1, v254, 36
	v_pk_mul_f32 v[64:65], v[154:155], v[52:53]
	v_lshlrev_b32_e32 v0, 1, v138
	v_mov_b64_e32 v[58:59], s[0:1]
	v_mad_i64_i32 v[58:59], s[0:1], v54, s52, v[58:59]
	s_lshl_b32 s0, s27, 1
	s_mov_b32 s1, s35
	v_lshl_add_u64 v[58:59], v[58:59], 0, s[0:1]
	v_lshl_add_u64 v[62:63], s[76:77], 1, v[58:59]
	v_mov_b32_e32 v58, v154
	v_mov_b32_e32 v59, v154
	v_pk_mul_f32 v[60:61], v[58:59], v[60:61]
	v_lshl_add_u64 v[52:53], v[62:63], 0, v[0:1]
	v_cvt_pk_bf16_f32 v62, v64, v65
	v_cvt_pk_bf16_f32 v63, v60, v61
	global_store_dwordx2 v[52:53], v[62:63], off
	s_nop 1
	v_mov_b64_e32 v[60:61], v[228:229]
	v_mov_b64_e32 v[62:63], v[230:231]
	v_mov_b32_e32 v51, v50
	v_pk_mul_f32 v[64:65], v[42:43], v[50:51]
	v_pk_mul_f32 v[60:61], v[64:65], v[60:61]
	v_pk_mul_f32 v[64:65], v[44:45], v[50:51]
	s_nop 0
	v_pk_mul_f32 v[62:63], v[64:65], v[62:63]
	s_and_saveexec_b64 s[0:1], vcc
	s_cbranch_execz .LBB0_1203
	v_readlane_b32 s4, v254, 6
	v_readlane_b32 s5, v254, 7
	s_nop 4
	global_load_dwordx4 v[64:67], v55, s[4:5] offset:64
	s_waitcnt vmcnt(0)
	v_pk_mul_f32 v[70:71], v[60:61], v[64:65] op_sel:[1,1] op_sel_hi:[1,0]
	v_mul_f32_e32 v0, v63, v67
	v_pk_mul_f32 v[68:69], v[60:61], v[64:65]
	v_pk_fma_f32 v[60:61], v[60:61], v[64:65], v[70:71] op_sel_hi:[0,1,1]
	v_pk_fma_f32 v[64:65], v[62:63], v[66:67], v[0:1] op_sel_hi:[1,1,0] neg_lo:[0,0,1] neg_hi:[0,0,1]
	v_mul_f32_e32 v0, v63, v66
	v_pk_fma_f32 v[66:67], v[62:63], v[66:67], v[0:1] op_sel:[0,1,0] op_sel_hi:[1,0,0]
	v_sub_f32_e32 v60, v68, v70
	v_mov_b32_e32 v62, v64
	v_mov_b32_e32 v63, v66
.LBB0_1203:
	s_or_b64 exec, exec, s[0:1]
	v_pk_mul_f32 v[58:59], v[58:59], v[62:63]
	v_pk_mul_f32 v[60:61], v[154:155], v[60:61]
	v_pk_mul_f32 v[62:63], v[38:39], v[50:51]
	v_cvt_pk_bf16_f32 v60, v60, v61
	v_cvt_pk_bf16_f32 v61, v58, v59
	global_store_dwordx2 v[52:53], v[60:61], off offset:32
	s_nop 1
	v_mov_b64_e32 v[58:59], v[232:233]
	v_mov_b64_e32 v[60:61], v[234:235]
	v_pk_mul_f32 v[58:59], v[62:63], v[58:59]
	v_pk_mul_f32 v[62:63], v[40:41], v[50:51]
	s_nop 0
	v_pk_mul_f32 v[62:63], v[62:63], v[60:61]
	s_and_saveexec_b64 s[0:1], vcc
	s_cbranch_execz .LBB0_1205
	global_load_dwordx4 v[64:67], v[142:143], off
	s_waitcnt vmcnt(0)
	v_pk_mul_f32 v[68:69], v[58:59], v[64:65] op_sel:[1,1] op_sel_hi:[1,0]
	v_mul_f32_e32 v0, v63, v67
	v_pk_mul_f32 v[60:61], v[58:59], v[64:65]
	v_pk_fma_f32 v[58:59], v[58:59], v[64:65], v[68:69] op_sel_hi:[0,1,1]
	v_pk_fma_f32 v[64:65], v[62:63], v[66:67], v[0:1] op_sel_hi:[1,1,0] neg_lo:[0,0,1] neg_hi:[0,0,1]
	v_mul_f32_e32 v0, v63, v66
	v_pk_fma_f32 v[66:67], v[62:63], v[66:67], v[0:1] op_sel:[0,1,0] op_sel_hi:[1,0,0]
	v_sub_f32_e32 v58, v60, v68
	v_mov_b32_e32 v62, v64
	v_mov_b32_e32 v63, v66
.LBB0_1205:
	s_or_b64 exec, exec, s[0:1]
	v_mov_b32_e32 v60, v154
	v_mov_b32_e32 v61, v154
	v_pk_mul_f32 v[62:63], v[60:61], v[62:63]
	v_pk_mul_f32 v[58:59], v[154:155], v[58:59]
	v_pk_mul_f32 v[64:65], v[36:37], v[50:51]
	v_cvt_pk_bf16_f32 v58, v58, v59
	v_cvt_pk_bf16_f32 v59, v62, v63
	global_store_dwordx2 v[52:53], v[58:59], off offset:64
	s_nop 1
	v_mov_b64_e32 v[56:57], v[236:237]
	v_mov_b64_e32 v[58:59], v[238:239]
	v_pk_mul_f32 v[62:63], v[34:35], v[50:51]
	v_pk_mul_f32 v[50:51], v[62:63], v[56:57]
	v_pk_mul_f32 v[56:57], v[64:65], v[58:59]
	s_and_saveexec_b64 s[0:1], vcc
	s_cbranch_execz .LBB0_1207
	global_load_dwordx4 v[62:65], v[142:143], off offset:64
	s_waitcnt vmcnt(0)
	v_pk_mul_f32 v[66:67], v[50:51], v[62:63] op_sel:[1,1] op_sel_hi:[1,0]
	v_mul_f32_e32 v0, v57, v65
	v_pk_mul_f32 v[58:59], v[50:51], v[62:63]
	v_pk_fma_f32 v[50:51], v[50:51], v[62:63], v[66:67] op_sel_hi:[0,1,1]
	v_pk_fma_f32 v[62:63], v[56:57], v[64:65], v[0:1] op_sel_hi:[1,1,0] neg_lo:[0,0,1] neg_hi:[0,0,1]
	v_mul_f32_e32 v0, v57, v64
	v_pk_fma_f32 v[64:65], v[56:57], v[64:65], v[0:1] op_sel:[0,1,0] op_sel_hi:[1,0,0]
	v_sub_f32_e32 v50, v58, v66
	v_mov_b32_e32 v56, v62
	v_mov_b32_e32 v57, v64

.LBB0_1229:
	s_and_b64 vcc, exec, s[0:1]
	s_cbranch_vccz .LBB0_1231
	s_and_b64 s[0:1], s[68:69], exec
	v_readlane_b32 s0, v254, 25
	v_readlane_b32 s4, v254, 29
	v_readlane_b32 s1, v254, 26
	v_readlane_b32 s5, v254, 30
	v_ashrrev_i32_e32 v55, 31, v54
	s_cselect_b32 s1, s1, s5
	s_cselect_b32 s0, s0, s4
	v_lshlrev_b64 v[50:51], 10, v[54:55]
	v_lshl_add_u64 v[50:51], s[0:1], 0, v[50:51]
	s_lshl_b32 s0, s25, 2
	s_mov_b32 s1, s35
	v_lshl_add_u64 v[56:57], v[50:51], 0, s[0:1]
	v_lshl_add_u64 v[50:51], s[36:37], 2, v[148:149]
	s_nop 1
	v_mov_b64_e32 v[52:53], v[224:225]
	v_mov_b64_e32 v[54:55], v[226:227]
	v_mul_f32_e32 v0, 0xbfb8aa3b, v46
	v_exp_f32_e32 v0, v0
	v_sub_f32_e32 v59, 1.0, v53
	v_add_f32_e32 v0, 1.0, v0
	v_rcp_f32_e32 v46, v0
	v_mul_f32_e32 v0, 0xbfb8aa3b, v47
	v_exp_f32_e32 v0, v0
	v_sub_f32_e32 v58, 1.0, v52
	v_sub_f32_e32 v61, 1.0, v55
	v_sub_f32_e32 v60, 1.0, v54
	v_add_f32_e32 v0, 1.0, v0
	v_rcp_f32_e32 v47, v0
	v_mul_f32_e32 v0, 0xbfb8aa3b, v48
	v_exp_f32_e32 v0, v0
	v_pk_fma_f32 v[52:53], v[46:47], v[58:59], v[52:53]
	v_add_f32_e32 v0, 1.0, v0
	v_rcp_f32_e32 v48, v0
	v_mul_f32_e32 v0, 0xbfb8aa3b, v49
	v_exp_f32_e32 v0, v0
	s_nop 0
	v_add_f32_e32 v0, 1.0, v0
	v_rcp_f32_e32 v49, v0
	v_lshlrev_b32_e32 v0, 2, v138
	v_lshl_add_u64 v[46:47], v[56:57], 0, v[0:1]
	v_mul_f32_e32 v0, 0xbfb8aa3b, v42
	v_pk_fma_f32 v[54:55], v[48:49], v[60:61], v[54:55]
	global_store_dwordx4 v[46:47], v[52:55], off
	s_nop 1
	v_mov_b64_e32 v[52:53], v[228:229]
	v_mov_b64_e32 v[54:55], v[230:231]
	v_exp_f32_e32 v0, v0
	v_sub_f32_e32 v49, 1.0, v53
	v_add_f32_e32 v0, 1.0, v0
	v_rcp_f32_e32 v42, v0
	v_mul_f32_e32 v0, 0xbfb8aa3b, v43
	v_exp_f32_e32 v0, v0
	v_sub_f32_e32 v48, 1.0, v52
	v_sub_f32_e32 v57, 1.0, v55
	v_sub_f32_e32 v56, 1.0, v54
	v_add_f32_e32 v0, 1.0, v0
	v_rcp_f32_e32 v43, v0
	v_mul_f32_e32 v0, 0xbfb8aa3b, v44
	v_exp_f32_e32 v0, v0
	v_pk_fma_f32 v[42:43], v[42:43], v[48:49], v[52:53]
	v_add_f32_e32 v0, 1.0, v0
	v_rcp_f32_e32 v44, v0
	v_mul_f32_e32 v0, 0xbfb8aa3b, v45
	v_exp_f32_e32 v0, v0
	s_nop 0
	v_add_f32_e32 v0, 1.0, v0
	v_rcp_f32_e32 v45, v0
	v_mul_f32_e32 v0, 0xbfb8aa3b, v38
	v_exp_f32_e32 v0, v0
	v_pk_fma_f32 v[44:45], v[44:45], v[56:57], v[54:55]
	global_store_dwordx4 v[46:47], v[42:45], off offset:64
	s_nop 1
	v_mov_b64_e32 v[42:43], v[232:233]
	v_mov_b64_e32 v[44:45], v[234:235]
	v_add_f32_e32 v0, 1.0, v0
	v_rcp_f32_e32 v38, v0
	v_mul_f32_e32 v0, 0xbfb8aa3b, v39
	v_exp_f32_e32 v0, v0
	v_sub_f32_e32 v49, 1.0, v43
	v_add_f32_e32 v0, 1.0, v0
	v_rcp_f32_e32 v39, v0
	v_mul_f32_e32 v0, 0xbfb8aa3b, v40
	v_exp_f32_e32 v0, v0
	v_sub_f32_e32 v48, 1.0, v42
	v_sub_f32_e32 v53, 1.0, v45
	v_sub_f32_e32 v52, 1.0, v44
	v_add_f32_e32 v0, 1.0, v0
	v_rcp_f32_e32 v40, v0
	v_mul_f32_e32 v0, 0xbfb8aa3b, v41
	v_exp_f32_e32 v0, v0
	v_pk_fma_f32 v[38:39], v[38:39], v[48:49], v[42:43]
	v_add_f32_e32 v0, 1.0, v0
	v_rcp_f32_e32 v41, v0
	v_mul_f32_e32 v0, 0xbfb8aa3b, v34
	v_exp_f32_e32 v0, v0
	v_pk_fma_f32 v[40:41], v[40:41], v[52:53], v[44:45]
	global_store_dwordx4 v[46:47], v[38:41], off offset:128
	s_nop 1
	v_mov_b64_e32 v[38:39], v[236:237]
	v_mov_b64_e32 v[40:41], v[238:239]
	v_add_f32_e32 v0, 1.0, v0
	v_rcp_f32_e32 v34, v0
	v_mul_f32_e32 v0, 0xbfb8aa3b, v35
	v_exp_f32_e32 v0, v0
	v_sub_f32_e32 v43, 1.0, v39
	v_add_f32_e32 v0, 1.0, v0
	v_rcp_f32_e32 v35, v0
	v_mul_f32_e32 v0, 0xbfb8aa3b, v36
	v_exp_f32_e32 v0, v0
	v_sub_f32_e32 v42, 1.0, v38
	v_sub_f32_e32 v45, 1.0, v41
	v_sub_f32_e32 v44, 1.0, v40
	v_add_f32_e32 v0, 1.0, v0
	v_rcp_f32_e32 v36, v0
	v_mul_f32_e32 v0, 0xbfb8aa3b, v37
	v_exp_f32_e32 v0, v0
	v_pk_fma_f32 v[34:35], v[34:35], v[42:43], v[38:39]
	v_add_f32_e32 v0, 1.0, v0
	v_rcp_f32_e32 v37, v0
	s_nop 0
	v_pk_fma_f32 v[36:37], v[36:37], v[44:45], v[40:41]
	global_store_dwordx4 v[46:47], v[34:37], off offset:192

.LBB0_1246:
	s_and_b64 vcc, exec, s[0:1]
	s_cbranch_vccz .LBB0_1256
	v_mul_f32_e32 v0, v31, v31
	v_fmac_f32_e32 v0, v30, v30
	v_fmac_f32_e32 v0, v32, v32
	v_fmac_f32_e32 v0, v33, v33
	v_fmac_f32_e32 v0, v26, v26
	v_fmac_f32_e32 v0, v27, v27
	v_fmac_f32_e32 v0, v28, v28
	v_fmac_f32_e32 v0, v29, v29
	v_fmac_f32_e32 v0, v22, v22
	v_fmac_f32_e32 v0, v23, v23
	v_pk_mul_f32 v[34:35], v[24:25], v[24:25]
	v_pk_mul_f32 v[36:37], v[18:19], v[18:19]
	v_add_f32_e32 v0, v34, v0
	v_add_f32_e32 v0, v35, v0
	v_add_f32_e32 v0, v36, v0
	v_pk_mul_f32 v[34:35], v[20:21], v[20:21]
	v_add_f32_e32 v0, v37, v0
	v_add_f32_e32 v0, v34, v0
	v_add_f32_e32 v0, v35, v0
	v_and_b32_e32 v35, 64, v214
	v_xor_b32_e32 v34, 16, v214
	v_add_u32_e32 v35, 64, v35
	v_cmp_lt_i32_e32 vcc, v34, v35
	s_and_b64 s[0:1], s[42:43], exec
	s_cselect_b32 s1, s18, s20
	v_cndmask_b32_e32 v34, v214, v34, vcc
	v_lshlrev_b32_e32 v34, 2, v34
	ds_bpermute_b32 v34, v34, v0
	s_cselect_b32 s0, s17, s19
	s_lshr_b32 s4, s28, 2
	s_and_b32 s4, s4, 0x7f0
	s_waitcnt lgkmcnt(0)
	v_add_f32_e32 v0, v0, v34
	v_xor_b32_e32 v34, 32, v214
	v_cmp_lt_i32_e32 vcc, v34, v35
	v_or_b32_e32 v35, s4, v167
	v_lshlrev_b32_e32 v39, 3, v35
	v_cndmask_b32_e32 v34, v214, v34, vcc
	v_lshlrev_b32_e32 v34, 2, v34
	ds_bpermute_b32 v34, v34, v0
	v_cmp_gt_i32_e32 vcc, s81, v38
	s_waitcnt lgkmcnt(0)
	v_add_f32_e32 v0, v0, v34
	v_fmamk_f32 v0, v0, 0x3c800000, v208
	v_rsq_f32_e32 v34, v0
	v_lshlrev_b32_e32 v0, 2, v138
	s_nop 1
	v_mov_b64_e32 v[40:41], v[224:225]
	v_mov_b64_e32 v[42:43], v[226:227]
	v_pk_mul_f32 v[36:37], v[30:31], v[34:35] op_sel_hi:[1,0]
	v_pk_mul_f32 v[36:37], v[40:41], v[36:37]
	v_pk_mul_f32 v[40:41], v[32:33], v[34:35] op_sel_hi:[1,0]
	s_nop 0
	v_pk_mul_f32 v[44:45], v[42:43], v[40:41]
	s_and_saveexec_b64 s[4:5], vcc
	s_cbranch_execz .LBB0_1249
	v_readlane_b32 s6, v254, 6
	v_readlane_b32 s7, v254, 7
	s_nop 4
	global_load_dwordx4 v[40:43], v39, s[6:7]
	s_waitcnt vmcnt(0)
	v_pk_mul_f32 v[48:49], v[36:37], v[40:41] op_sel:[1,1] op_sel_hi:[1,0]
	v_pk_mul_f32 v[46:47], v[36:37], v[40:41]
	v_pk_fma_f32 v[36:37], v[36:37], v[40:41], v[48:49] op_sel_hi:[0,1,1]
	v_mul_f32_e32 v36, v45, v43
	v_pk_fma_f32 v[40:41], v[44:45], v[42:43], v[36:37] op_sel_hi:[1,1,0] neg_lo:[0,0,1] neg_hi:[0,0,1]
	v_mul_f32_e32 v36, v45, v42
	v_pk_fma_f32 v[42:43], v[44:45], v[42:43], v[36:37] op_sel:[0,1,0] op_sel_hi:[1,0,0]
	v_sub_f32_e32 v36, v46, v48
	v_mov_b32_e32 v44, v40
	v_mov_b32_e32 v45, v42
.LBB0_1249:
	s_or_b64 exec, exec, s[4:5]
	v_lshl_add_u64 v[40:41], s[0:1], 0, v[0:1]
	v_readlane_b32 s0, v254, 35
	v_readlane_b32 s1, v254, 36
	v_pk_mul_f32 v[48:49], v[154:155], v[36:37]
	v_lshlrev_b32_e32 v0, 1, v138
	v_mov_b64_e32 v[42:43], s[0:1]
	v_mad_i64_i32 v[42:43], s[0:1], v38, s52, v[42:43]
	s_lshl_b32 s0, s27, 1
	s_mov_b32 s1, s35
	v_lshl_add_u64 v[42:43], v[42:43], 0, s[0:1]
	v_lshl_add_u64 v[46:47], s[76:77], 1, v[42:43]
	v_mov_b32_e32 v42, v154
	v_mov_b32_e32 v43, v154
	v_pk_mul_f32 v[44:45], v[42:43], v[44:45]
	v_lshl_add_u64 v[36:37], v[46:47], 0, v[0:1]
	v_cvt_pk_bf16_f32 v46, v48, v49
	v_cvt_pk_bf16_f32 v47, v44, v45
	global_store_dwordx2 v[36:37], v[46:47], off
	s_nop 1
	v_mov_b64_e32 v[44:45], v[228:229]
	v_mov_b64_e32 v[46:47], v[230:231]
	v_mov_b32_e32 v35, v34
	v_pk_mul_f32 v[48:49], v[26:27], v[34:35]
	v_pk_mul_f32 v[44:45], v[48:49], v[44:45]
	v_pk_mul_f32 v[48:49], v[28:29], v[34:35]
	s_nop 0
	v_pk_mul_f32 v[46:47], v[48:49], v[46:47]
	s_and_saveexec_b64 s[0:1], vcc
	s_cbranch_execz .LBB0_1251
	v_readlane_b32 s4, v254, 6
	v_readlane_b32 s5, v254, 7
	s_nop 4
	global_load_dwordx4 v[48:51], v39, s[4:5] offset:64
	s_waitcnt vmcnt(0)
	v_pk_mul_f32 v[54:55], v[44:45], v[48:49] op_sel:[1,1] op_sel_hi:[1,0]
	v_mul_f32_e32 v0, v47, v51
	v_pk_mul_f32 v[52:53], v[44:45], v[48:49]
	v_pk_fma_f32 v[44:45], v[44:45], v[48:49], v[54:55] op_sel_hi:[0,1,1]
	v_pk_fma_f32 v[48:49], v[46:47], v[50:51], v[0:1] op_sel_hi:[1,1,0] neg_lo:[0,0,1] neg_hi:[0,0,1]
	v_mul_f32_e32 v0, v47, v50
	v_pk_fma_f32 v[50:51], v[46:47], v[50:51], v[0:1] op_sel:[0,1,0] op_sel_hi:[1,0,0]
	v_sub_f32_e32 v44, v52, v54
	v_mov_b32_e32 v46, v48
	v_mov_b32_e32 v47, v50
.LBB0_1251:
	s_or_b64 exec, exec, s[0:1]
	v_pk_mul_f32 v[42:43], v[42:43], v[46:47]
	v_pk_mul_f32 v[44:45], v[154:155], v[44:45]
	v_pk_mul_f32 v[46:47], v[22:23], v[34:35]
	v_cvt_pk_bf16_f32 v44, v44, v45
	v_cvt_pk_bf16_f32 v45, v42, v43
	global_store_dwordx2 v[36:37], v[44:45], off offset:32
	s_nop 1
	v_mov_b64_e32 v[42:43], v[232:233]
	v_mov_b64_e32 v[44:45], v[234:235]
	v_pk_mul_f32 v[42:43], v[46:47], v[42:43]
	v_pk_mul_f32 v[46:47], v[24:25], v[34:35]
	s_nop 0
	v_pk_mul_f32 v[46:47], v[46:47], v[44:45]
	s_and_saveexec_b64 s[0:1], vcc
	s_cbranch_execz .LBB0_1253
	global_load_dwordx4 v[48:51], v[144:145], off
	s_waitcnt vmcnt(0)
	v_pk_mul_f32 v[52:53], v[42:43], v[48:49] op_sel:[1,1] op_sel_hi:[1,0]
	v_mul_f32_e32 v0, v47, v51
	v_pk_mul_f32 v[44:45], v[42:43], v[48:49]
	v_pk_fma_f32 v[42:43], v[42:43], v[48:49], v[52:53] op_sel_hi:[0,1,1]
	v_pk_fma_f32 v[48:49], v[46:47], v[50:51], v[0:1] op_sel_hi:[1,1,0] neg_lo:[0,0,1] neg_hi:[0,0,1]
	v_mul_f32_e32 v0, v47, v50
	v_pk_fma_f32 v[50:51], v[46:47], v[50:51], v[0:1] op_sel:[0,1,0] op_sel_hi:[1,0,0]
	v_sub_f32_e32 v42, v44, v52
	v_mov_b32_e32 v46, v48
	v_mov_b32_e32 v47, v50
.LBB0_1253:
	s_or_b64 exec, exec, s[0:1]
	v_mov_b32_e32 v44, v154
	v_mov_b32_e32 v45, v154
	v_pk_mul_f32 v[46:47], v[44:45], v[46:47]
	v_pk_mul_f32 v[42:43], v[154:155], v[42:43]
	v_pk_mul_f32 v[48:49], v[20:21], v[34:35]
	v_cvt_pk_bf16_f32 v42, v42, v43
	v_cvt_pk_bf16_f32 v43, v46, v47
	global_store_dwordx2 v[36:37], v[42:43], off offset:64
	s_nop 1
	v_mov_b64_e32 v[40:41], v[236:237]
	v_mov_b64_e32 v[42:43], v[238:239]
	v_pk_mul_f32 v[46:47], v[18:19], v[34:35]
	v_pk_mul_f32 v[34:35], v[46:47], v[40:41]
	v_pk_mul_f32 v[40:41], v[48:49], v[42:43]
	s_and_saveexec_b64 s[0:1], vcc
	s_cbranch_execz .LBB0_1255
	global_load_dwordx4 v[46:49], v[144:145], off offset:64
	s_waitcnt vmcnt(0)
	v_pk_mul_f32 v[50:51], v[34:35], v[46:47] op_sel:[1,1] op_sel_hi:[1,0]
	v_mul_f32_e32 v0, v41, v49
	v_pk_mul_f32 v[42:43], v[34:35], v[46:47]
	v_pk_fma_f32 v[34:35], v[34:35], v[46:47], v[50:51] op_sel_hi:[0,1,1]
	v_pk_fma_f32 v[46:47], v[40:41], v[48:49], v[0:1] op_sel_hi:[1,1,0] neg_lo:[0,0,1] neg_hi:[0,0,1]
	v_mul_f32_e32 v0, v41, v48
	v_pk_fma_f32 v[48:49], v[40:41], v[48:49], v[0:1] op_sel:[0,1,0] op_sel_hi:[1,0,0]
	v_sub_f32_e32 v34, v42, v50
	v_mov_b32_e32 v40, v46
	v_mov_b32_e32 v41, v48

.LBB0_1277:
	s_and_b64 vcc, exec, s[0:1]
	s_cbranch_vccz .LBB0_1279
	s_and_b64 s[0:1], s[68:69], exec
	v_readlane_b32 s0, v254, 25
	v_readlane_b32 s4, v254, 29
	v_readlane_b32 s1, v254, 26
	v_readlane_b32 s5, v254, 30
	v_ashrrev_i32_e32 v39, 31, v38
	s_cselect_b32 s1, s1, s5
	s_cselect_b32 s0, s0, s4
	v_lshlrev_b64 v[34:35], 10, v[38:39]
	v_lshl_add_u64 v[34:35], s[0:1], 0, v[34:35]
	s_lshl_b32 s0, s25, 2
	s_mov_b32 s1, s35
	v_lshl_add_u64 v[40:41], v[34:35], 0, s[0:1]
	v_lshl_add_u64 v[34:35], s[36:37], 2, v[148:149]
	s_nop 1
	v_mov_b64_e32 v[36:37], v[224:225]
	v_mov_b64_e32 v[38:39], v[226:227]
	v_mul_f32_e32 v0, 0xbfb8aa3b, v30
	v_exp_f32_e32 v0, v0
	v_sub_f32_e32 v43, 1.0, v37
	v_add_f32_e32 v0, 1.0, v0
	v_rcp_f32_e32 v30, v0
	v_mul_f32_e32 v0, 0xbfb8aa3b, v31
	v_exp_f32_e32 v0, v0
	v_sub_f32_e32 v42, 1.0, v36
	v_sub_f32_e32 v45, 1.0, v39
	v_sub_f32_e32 v44, 1.0, v38
	v_add_f32_e32 v0, 1.0, v0
	v_rcp_f32_e32 v31, v0
	v_mul_f32_e32 v0, 0xbfb8aa3b, v32
	v_exp_f32_e32 v0, v0
	v_pk_fma_f32 v[36:37], v[30:31], v[42:43], v[36:37]
	v_add_f32_e32 v0, 1.0, v0
	v_rcp_f32_e32 v32, v0
	v_mul_f32_e32 v0, 0xbfb8aa3b, v33
	v_exp_f32_e32 v0, v0
	s_nop 0
	v_add_f32_e32 v0, 1.0, v0
	v_rcp_f32_e32 v33, v0
	v_lshlrev_b32_e32 v0, 2, v138
	v_lshl_add_u64 v[30:31], v[40:41], 0, v[0:1]
	v_mul_f32_e32 v0, 0xbfb8aa3b, v26
	v_pk_fma_f32 v[38:39], v[32:33], v[44:45], v[38:39]
	global_store_dwordx4 v[30:31], v[36:39], off
	s_nop 1
	v_mov_b64_e32 v[36:37], v[228:229]
	v_mov_b64_e32 v[38:39], v[230:231]
	v_exp_f32_e32 v0, v0
	v_sub_f32_e32 v33, 1.0, v37
	v_add_f32_e32 v0, 1.0, v0
	v_rcp_f32_e32 v26, v0
	v_mul_f32_e32 v0, 0xbfb8aa3b, v27
	v_exp_f32_e32 v0, v0
	v_sub_f32_e32 v32, 1.0, v36
	v_sub_f32_e32 v41, 1.0, v39
	v_sub_f32_e32 v40, 1.0, v38
	v_add_f32_e32 v0, 1.0, v0
	v_rcp_f32_e32 v27, v0
	v_mul_f32_e32 v0, 0xbfb8aa3b, v28
	v_exp_f32_e32 v0, v0
	v_pk_fma_f32 v[26:27], v[26:27], v[32:33], v[36:37]
	v_add_f32_e32 v0, 1.0, v0
	v_rcp_f32_e32 v28, v0
	v_mul_f32_e32 v0, 0xbfb8aa3b, v29
	v_exp_f32_e32 v0, v0
	s_nop 0
	v_add_f32_e32 v0, 1.0, v0
	v_rcp_f32_e32 v29, v0
	v_mul_f32_e32 v0, 0xbfb8aa3b, v22
	v_exp_f32_e32 v0, v0
	v_pk_fma_f32 v[28:29], v[28:29], v[40:41], v[38:39]
	global_store_dwordx4 v[30:31], v[26:29], off offset:64
	s_nop 1
	v_mov_b64_e32 v[26:27], v[232:233]
	v_mov_b64_e32 v[28:29], v[234:235]
	v_add_f32_e32 v0, 1.0, v0
	v_rcp_f32_e32 v22, v0
	v_mul_f32_e32 v0, 0xbfb8aa3b, v23
	v_exp_f32_e32 v0, v0
	v_sub_f32_e32 v33, 1.0, v27
	v_add_f32_e32 v0, 1.0, v0
	v_rcp_f32_e32 v23, v0
	v_mul_f32_e32 v0, 0xbfb8aa3b, v24
	v_exp_f32_e32 v0, v0
	v_sub_f32_e32 v32, 1.0, v26
	v_sub_f32_e32 v37, 1.0, v29
	v_sub_f32_e32 v36, 1.0, v28
	v_add_f32_e32 v0, 1.0, v0
	v_rcp_f32_e32 v24, v0
	v_mul_f32_e32 v0, 0xbfb8aa3b, v25
	v_exp_f32_e32 v0, v0
	v_pk_fma_f32 v[22:23], v[22:23], v[32:33], v[26:27]
	v_add_f32_e32 v0, 1.0, v0
	v_rcp_f32_e32 v25, v0
	v_mul_f32_e32 v0, 0xbfb8aa3b, v18
	v_exp_f32_e32 v0, v0
	v_pk_fma_f32 v[24:25], v[24:25], v[36:37], v[28:29]
	global_store_dwordx4 v[30:31], v[22:25], off offset:128
	s_nop 1
	v_mov_b64_e32 v[22:23], v[236:237]
	v_mov_b64_e32 v[24:25], v[238:239]
	v_add_f32_e32 v0, 1.0, v0
	v_rcp_f32_e32 v18, v0
	v_mul_f32_e32 v0, 0xbfb8aa3b, v19
	v_exp_f32_e32 v0, v0
	v_sub_f32_e32 v27, 1.0, v23
	v_add_f32_e32 v0, 1.0, v0
	v_rcp_f32_e32 v19, v0
	v_mul_f32_e32 v0, 0xbfb8aa3b, v20
	v_exp_f32_e32 v0, v0
	v_sub_f32_e32 v26, 1.0, v22
	v_sub_f32_e32 v29, 1.0, v25
	v_sub_f32_e32 v28, 1.0, v24
	v_add_f32_e32 v0, 1.0, v0
	v_rcp_f32_e32 v20, v0
	v_mul_f32_e32 v0, 0xbfb8aa3b, v21
	v_exp_f32_e32 v0, v0
	v_pk_fma_f32 v[18:19], v[18:19], v[26:27], v[22:23]
	v_add_f32_e32 v0, 1.0, v0
	v_rcp_f32_e32 v21, v0
	s_nop 0
	v_pk_fma_f32 v[20:21], v[20:21], v[28:29], v[24:25]
	global_store_dwordx4 v[30:31], v[18:21], off offset:192

.LBB0_1294:
	s_and_b64 vcc, exec, s[0:1]
	s_cbranch_vccz .LBB0_1304
	v_mul_f32_e32 v0, v15, v15
	v_fmac_f32_e32 v0, v14, v14
	v_fmac_f32_e32 v0, v16, v16
	v_fmac_f32_e32 v0, v17, v17
	v_fmac_f32_e32 v0, v10, v10
	v_fmac_f32_e32 v0, v11, v11
	v_fmac_f32_e32 v0, v12, v12
	v_fmac_f32_e32 v0, v13, v13
	v_fmac_f32_e32 v0, v6, v6
	v_fmac_f32_e32 v0, v7, v7
	v_pk_mul_f32 v[18:19], v[8:9], v[8:9]
	v_pk_mul_f32 v[20:21], v[2:3], v[2:3]
	v_add_f32_e32 v0, v18, v0
	v_add_f32_e32 v0, v19, v0
	v_add_f32_e32 v0, v20, v0
	v_pk_mul_f32 v[18:19], v[4:5], v[4:5]
	v_add_f32_e32 v0, v21, v0
	v_add_f32_e32 v0, v18, v0
	v_add_f32_e32 v0, v19, v0
	v_and_b32_e32 v19, 64, v214
	v_xor_b32_e32 v18, 16, v214
	v_add_u32_e32 v19, 64, v19
	v_cmp_lt_i32_e32 vcc, v18, v19
	s_and_b64 s[0:1], s[42:43], exec
	s_cselect_b32 s1, s18, s20
	v_cndmask_b32_e32 v18, v214, v18, vcc
	v_lshlrev_b32_e32 v18, 2, v18
	ds_bpermute_b32 v18, v18, v0
	s_cselect_b32 s0, s17, s19
	s_lshr_b32 s2, s28, 2
	s_and_b32 s2, s2, 0x7f0
	s_waitcnt lgkmcnt(0)
	v_add_f32_e32 v0, v0, v18
	v_xor_b32_e32 v18, 32, v214
	v_cmp_lt_i32_e32 vcc, v18, v19
	v_or_b32_e32 v19, s2, v167
	v_lshlrev_b32_e32 v23, 3, v19
	v_cndmask_b32_e32 v18, v214, v18, vcc
	v_lshlrev_b32_e32 v18, 2, v18
	ds_bpermute_b32 v18, v18, v0
	v_cmp_gt_i32_e32 vcc, s81, v22
	s_waitcnt lgkmcnt(0)
	v_add_f32_e32 v0, v0, v18
	v_fmamk_f32 v0, v0, 0x3c800000, v208
	v_rsq_f32_e32 v18, v0
	v_lshlrev_b32_e32 v0, 2, v138
	s_nop 1
	v_mov_b64_e32 v[24:25], v[224:225]
	v_mov_b64_e32 v[26:27], v[226:227]
	v_pk_mul_f32 v[20:21], v[14:15], v[18:19] op_sel_hi:[1,0]
	v_pk_mul_f32 v[20:21], v[24:25], v[20:21]
	v_pk_mul_f32 v[24:25], v[16:17], v[18:19] op_sel_hi:[1,0]
	s_nop 0
	v_pk_mul_f32 v[28:29], v[26:27], v[24:25]
	s_and_saveexec_b64 s[2:3], vcc
	s_cbranch_execz .LBB0_1297
	v_readlane_b32 s4, v254, 6
	v_readlane_b32 s5, v254, 7
	s_nop 4
	global_load_dwordx4 v[24:27], v23, s[4:5]
	s_waitcnt vmcnt(0)
	v_pk_mul_f32 v[32:33], v[20:21], v[24:25] op_sel:[1,1] op_sel_hi:[1,0]
	v_pk_mul_f32 v[30:31], v[20:21], v[24:25]
	v_pk_fma_f32 v[20:21], v[20:21], v[24:25], v[32:33] op_sel_hi:[0,1,1]
	v_mul_f32_e32 v20, v29, v27
	v_pk_fma_f32 v[24:25], v[28:29], v[26:27], v[20:21] op_sel_hi:[1,1,0] neg_lo:[0,0,1] neg_hi:[0,0,1]
	v_mul_f32_e32 v20, v29, v26
	v_pk_fma_f32 v[26:27], v[28:29], v[26:27], v[20:21] op_sel:[0,1,0] op_sel_hi:[1,0,0]
	v_sub_f32_e32 v20, v30, v32
	v_mov_b32_e32 v28, v24
	v_mov_b32_e32 v29, v26
.LBB0_1297:
	s_or_b64 exec, exec, s[2:3]
	v_lshl_add_u64 v[24:25], s[0:1], 0, v[0:1]
	v_readlane_b32 s0, v254, 35
	v_readlane_b32 s1, v254, 36
	s_lshl_b32 s34, s27, 1
	v_pk_mul_f32 v[32:33], v[154:155], v[20:21]
	v_mov_b64_e32 v[26:27], s[0:1]
	v_mad_i64_i32 v[26:27], s[0:1], v22, s52, v[26:27]
	v_lshl_add_u64 v[26:27], v[26:27], 0, s[34:35]
	v_lshl_add_u64 v[30:31], s[76:77], 1, v[26:27]
	v_mov_b32_e32 v26, v154
	v_mov_b32_e32 v27, v154
	v_pk_mul_f32 v[28:29], v[26:27], v[28:29]
	v_lshlrev_b32_e32 v0, 1, v138
	v_lshl_add_u64 v[20:21], v[30:31], 0, v[0:1]
	v_cvt_pk_bf16_f32 v30, v32, v33
	v_cvt_pk_bf16_f32 v31, v28, v29
	global_store_dwordx2 v[20:21], v[30:31], off
	s_nop 1
	v_mov_b64_e32 v[28:29], v[228:229]
	v_mov_b64_e32 v[30:31], v[230:231]
	v_mov_b32_e32 v19, v18
	v_pk_mul_f32 v[32:33], v[10:11], v[18:19]
	v_pk_mul_f32 v[28:29], v[32:33], v[28:29]
	v_pk_mul_f32 v[32:33], v[12:13], v[18:19]
	s_nop 0
	v_pk_mul_f32 v[30:31], v[32:33], v[30:31]
	s_and_saveexec_b64 s[0:1], vcc
	s_cbranch_execz .LBB0_1299
	v_readlane_b32 s2, v254, 6
	v_readlane_b32 s3, v254, 7
	s_nop 4
	global_load_dwordx4 v[32:35], v23, s[2:3] offset:64
	s_waitcnt vmcnt(0)
	v_pk_mul_f32 v[38:39], v[28:29], v[32:33] op_sel:[1,1] op_sel_hi:[1,0]
	v_mul_f32_e32 v0, v31, v35
	v_pk_mul_f32 v[36:37], v[28:29], v[32:33]
	v_pk_fma_f32 v[28:29], v[28:29], v[32:33], v[38:39] op_sel_hi:[0,1,1]
	v_pk_fma_f32 v[32:33], v[30:31], v[34:35], v[0:1] op_sel_hi:[1,1,0] neg_lo:[0,0,1] neg_hi:[0,0,1]
	v_mul_f32_e32 v0, v31, v34
	v_pk_fma_f32 v[34:35], v[30:31], v[34:35], v[0:1] op_sel:[0,1,0] op_sel_hi:[1,0,0]
	v_sub_f32_e32 v28, v36, v38
	v_mov_b32_e32 v30, v32
	v_mov_b32_e32 v31, v34
.LBB0_1299:
	s_or_b64 exec, exec, s[0:1]
	v_pk_mul_f32 v[26:27], v[26:27], v[30:31]
	v_pk_mul_f32 v[28:29], v[154:155], v[28:29]
	v_pk_mul_f32 v[30:31], v[6:7], v[18:19]
	v_cvt_pk_bf16_f32 v28, v28, v29
	v_cvt_pk_bf16_f32 v29, v26, v27
	global_store_dwordx2 v[20:21], v[28:29], off offset:32
	s_nop 1
	v_mov_b64_e32 v[26:27], v[232:233]
	v_mov_b64_e32 v[28:29], v[234:235]
	v_pk_mul_f32 v[26:27], v[30:31], v[26:27]
	v_pk_mul_f32 v[30:31], v[8:9], v[18:19]
	s_nop 0
	v_pk_mul_f32 v[30:31], v[30:31], v[28:29]
	s_and_saveexec_b64 s[0:1], vcc
	s_cbranch_execz .LBB0_1301
	global_load_dwordx4 v[32:35], v[146:147], off
	s_waitcnt vmcnt(0)
	v_pk_mul_f32 v[36:37], v[26:27], v[32:33] op_sel:[1,1] op_sel_hi:[1,0]
	v_mul_f32_e32 v0, v31, v35
	v_pk_mul_f32 v[28:29], v[26:27], v[32:33]
	v_pk_fma_f32 v[26:27], v[26:27], v[32:33], v[36:37] op_sel_hi:[0,1,1]
	v_pk_fma_f32 v[32:33], v[30:31], v[34:35], v[0:1] op_sel_hi:[1,1,0] neg_lo:[0,0,1] neg_hi:[0,0,1]
	v_mul_f32_e32 v0, v31, v34
	v_pk_fma_f32 v[34:35], v[30:31], v[34:35], v[0:1] op_sel:[0,1,0] op_sel_hi:[1,0,0]
	v_sub_f32_e32 v26, v28, v36
	v_mov_b32_e32 v30, v32
	v_mov_b32_e32 v31, v34
.LBB0_1301:
	s_or_b64 exec, exec, s[0:1]
	v_mov_b32_e32 v28, v154
	v_mov_b32_e32 v29, v154
	v_pk_mul_f32 v[30:31], v[28:29], v[30:31]
	v_pk_mul_f32 v[26:27], v[154:155], v[26:27]
	v_pk_mul_f32 v[32:33], v[4:5], v[18:19]
	v_cvt_pk_bf16_f32 v26, v26, v27
	v_cvt_pk_bf16_f32 v27, v30, v31
	global_store_dwordx2 v[20:21], v[26:27], off offset:64
	s_nop 1
	v_mov_b64_e32 v[24:25], v[236:237]
	v_mov_b64_e32 v[26:27], v[238:239]
	v_pk_mul_f32 v[30:31], v[2:3], v[18:19]
	v_pk_mul_f32 v[18:19], v[30:31], v[24:25]
	v_pk_mul_f32 v[24:25], v[32:33], v[26:27]
	s_and_saveexec_b64 s[0:1], vcc
	s_cbranch_execz .LBB0_1303
	global_load_dwordx4 v[30:33], v[146:147], off offset:64
	s_waitcnt vmcnt(0)
	v_pk_mul_f32 v[34:35], v[18:19], v[30:31] op_sel:[1,1] op_sel_hi:[1,0]
	v_mul_f32_e32 v0, v25, v33
	v_pk_mul_f32 v[26:27], v[18:19], v[30:31]
	v_pk_fma_f32 v[18:19], v[18:19], v[30:31], v[34:35] op_sel_hi:[0,1,1]
	v_pk_fma_f32 v[30:31], v[24:25], v[32:33], v[0:1] op_sel_hi:[1,1,0] neg_lo:[0,0,1] neg_hi:[0,0,1]
	v_mul_f32_e32 v0, v25, v32
	v_pk_fma_f32 v[32:33], v[24:25], v[32:33], v[0:1] op_sel:[0,1,0] op_sel_hi:[1,0,0]
	v_sub_f32_e32 v18, v26, v34
	v_mov_b32_e32 v24, v30
	v_mov_b32_e32 v25, v32

.LBB0_1325:
	s_and_b64 vcc, exec, s[0:1]
	s_cbranch_vccz .LBB0_1327
	v_lshl_add_u64 v[24:25], s[36:37], 2, v[148:149]
	s_nop 1
	v_mov_b64_e32 v[18:19], v[224:225]
	v_mov_b64_e32 v[20:21], v[226:227]
	s_and_b64 s[0:1], s[68:69], exec
	v_mul_f32_e32 v26, 0xbfb8aa3b, v14
	v_mul_f32_e32 v27, 0xbfb8aa3b, v15
	v_mul_f32_e32 v16, 0xbfb8aa3b, v16
	v_mul_f32_e32 v17, 0xbfb8aa3b, v17
	v_readlane_b32 s0, v254, 25
	v_readlane_b32 s2, v254, 29
	v_ashrrev_i32_e32 v23, 31, v22
	v_readlane_b32 s1, v254, 26
	v_readlane_b32 s3, v254, 30
	v_exp_f32_e32 v26, v26
	v_exp_f32_e32 v27, v27
	v_exp_f32_e32 v16, v16
	v_exp_f32_e32 v17, v17
	s_cselect_b32 s1, s1, s3
	s_cselect_b32 s0, s0, s2
	v_lshlrev_b64 v[14:15], 10, v[22:23]
	s_lshl_b32 s34, s25, 2
	v_lshl_add_u64 v[14:15], s[0:1], 0, v[14:15]
	v_lshlrev_b32_e32 v0, 2, v138
	v_lshl_add_u64 v[14:15], v[14:15], 0, s[34:35]
	v_lshl_add_u64 v[22:23], v[14:15], 0, v[0:1]
	v_add_f32_e32 v0, 1.0, v26
	v_add_f32_e32 v15, 1.0, v27
	v_add_f32_e32 v16, 1.0, v16
	v_add_f32_e32 v17, 1.0, v17
	v_rcp_f32_e32 v14, v0
	v_rcp_f32_e32 v15, v15
	v_rcp_f32_e32 v16, v16
	v_rcp_f32_e32 v17, v17
	v_mul_f32_e32 v0, 0xbfb8aa3b, v10
	v_mul_f32_e32 v10, 0xbfb8aa3b, v11
	v_mul_f32_e32 v11, 0xbfb8aa3b, v12
	v_mul_f32_e32 v12, 0xbfb8aa3b, v13
	v_exp_f32_e32 v0, v0
	v_exp_f32_e32 v10, v10
	v_exp_f32_e32 v11, v11
	v_exp_f32_e32 v12, v12
	v_add_f32_e32 v0, 1.0, v0
	v_add_f32_e32 v13, 1.0, v10
	v_rcp_f32_e32 v10, v0
	v_mul_f32_e32 v0, 0xbfb8aa3b, v6
	v_mul_f32_e32 v6, 0xbfb8aa3b, v7
	v_mul_f32_e32 v7, 0xbfb8aa3b, v8
	v_mul_f32_e32 v8, 0xbfb8aa3b, v9
	v_exp_f32_e32 v0, v0
	v_exp_f32_e32 v6, v6
	v_exp_f32_e32 v7, v7
	v_exp_f32_e32 v8, v8
	v_add_f32_e32 v0, 1.0, v0
	v_add_f32_e32 v9, 1.0, v6
	v_rcp_f32_e32 v6, v0
	v_mul_f32_e32 v0, 0xbfb8aa3b, v2
	v_mul_f32_e32 v2, 0xbfb8aa3b, v3
	v_mul_f32_e32 v3, 0xbfb8aa3b, v4
	v_mul_f32_e32 v4, 0xbfb8aa3b, v5
	v_exp_f32_e32 v0, v0
	v_exp_f32_e32 v2, v2
	v_exp_f32_e32 v3, v3
	v_exp_f32_e32 v4, v4
	v_add_f32_e32 v0, 1.0, v0
	v_add_f32_e32 v5, 1.0, v2
	v_rcp_f32_e32 v2, v0
	v_sub_f32_e32 v27, 1.0, v19
	v_sub_f32_e32 v26, 1.0, v18
	v_sub_f32_e32 v29, 1.0, v21
	v_sub_f32_e32 v28, 1.0, v20
	v_pk_fma_f32 v[16:17], v[16:17], v[28:29], v[20:21]
	v_pk_fma_f32 v[14:15], v[14:15], v[26:27], v[18:19]
	global_store_dwordx4 v[22:23], v[14:17], off
	s_nop 1
	v_mov_b64_e32 v[14:15], v[228:229]
	v_mov_b64_e32 v[16:17], v[230:231]
	v_add_f32_e32 v18, 1.0, v11
	v_add_f32_e32 v19, 1.0, v12
	v_rcp_f32_e32 v11, v13
	v_rcp_f32_e32 v12, v18
	v_rcp_f32_e32 v13, v19
	v_sub_f32_e32 v19, 1.0, v15
	v_sub_f32_e32 v18, 1.0, v14
	v_sub_f32_e32 v21, 1.0, v17
	v_sub_f32_e32 v20, 1.0, v16
	v_pk_fma_f32 v[12:13], v[12:13], v[20:21], v[16:17]
	v_pk_fma_f32 v[10:11], v[10:11], v[18:19], v[14:15]
	global_store_dwordx4 v[22:23], v[10:13], off offset:64
	s_nop 1
	v_mov_b64_e32 v[10:11], v[232:233]
	v_mov_b64_e32 v[12:13], v[234:235]
	v_add_f32_e32 v14, 1.0, v7
	v_add_f32_e32 v15, 1.0, v8
	v_rcp_f32_e32 v7, v9
	v_rcp_f32_e32 v8, v14
	v_rcp_f32_e32 v9, v15
	v_sub_f32_e32 v15, 1.0, v11
	v_sub_f32_e32 v14, 1.0, v10
	v_sub_f32_e32 v17, 1.0, v13
	v_sub_f32_e32 v16, 1.0, v12
	v_pk_fma_f32 v[8:9], v[8:9], v[16:17], v[12:13]
	v_pk_fma_f32 v[6:7], v[6:7], v[14:15], v[10:11]
	global_store_dwordx4 v[22:23], v[6:9], off offset:128
	s_nop 1
	v_mov_b64_e32 v[6:7], v[236:237]
	v_mov_b64_e32 v[8:9], v[238:239]
	v_add_f32_e32 v10, 1.0, v3
	v_add_f32_e32 v11, 1.0, v4
	v_rcp_f32_e32 v3, v5
	v_rcp_f32_e32 v4, v10
	v_rcp_f32_e32 v5, v11
	v_sub_f32_e32 v11, 1.0, v7
	v_sub_f32_e32 v10, 1.0, v6
	v_sub_f32_e32 v13, 1.0, v9
	v_sub_f32_e32 v12, 1.0, v8
	v_pk_fma_f32 v[4:5], v[4:5], v[12:13], v[8:9]
	v_pk_fma_f32 v[2:3], v[2:3], v[10:11], v[6:7]
	global_store_dwordx4 v[22:23], v[2:5], off offset:192
